# K-loop: closing s_setprio 0 issued in the shadow of the segment's last MFMA (compute wave reaches the closing barrier one slot earlier)
# baseline (speedup 1.0000x reference)
; #define PG8_STAGE(bufoff, gbase, voff) do { _Pragma("unroll") for (int _i = 0; _i < 2; ++_i) \
;         __builtin_amdgcn_global_load_lds((const unsigned*)((const char*)(gbase) + (voff)[_i]), (LAS unsigned*)(lds + (bufoff) + ldsw + _i * 8192), 16, 0, 0); } while (0)
; #define PG8_LDA(dst, b, h) do { _Pragma("unroll") for (int m = 0; m < 4; ++m) _Pragma("unroll") for (int k = 0; k < 2; ++k) dst[m][k] = *(const LAS bf16x8*)(lds + PG8_SA(b, h) + aoff + m * 2048 + k * 1024); } while (0)
; #define PG8_LDB(dst, b, h) do { _Pragma("unroll") for (int n = 0; n < 2; ++n) _Pragma("unroll") for (int k = 0; k < 2; ++k) dst[n][k] = *(const LAS bf16x8*)(lds + PG8_SB(b, h) + boff + n * 2048 + k * 1024); } while (0)
; #define PG8_MMA(ai, bj, At, Bt) do { __builtin_amdgcn_s_setprio(1); _Pragma("unroll") for (int m = 0; m < 4; ++m) _Pragma("unroll") for (int n = 0; n < 2; ++n) _Pragma("unroll") for (int k = 0; k < 2; ++k) \
;         acc[ai][bj][m][n] = __builtin_amdgcn_mfma_f32_16x16x32_bf16(Bt[n][k], At[m][k], acc[ai][bj][m][n], 0, 0, 0); __builtin_amdgcn_s_setprio(0); } while (0)
; #define PG8_WAIT_V(n) asm volatile("s_waitcnt vmcnt(" #n ")" ::: "memory")
; #define PG8_WAIT_L(n) asm volatile("s_waitcnt lgkmcnt(" #n ")" ::: "memory")
; #define PG8_BAR __builtin_amdgcn_s_barrier()
; #define PG8_SCHED __builtin_amdgcn_sched_barrier(0)
; template <class Epi, int AMODE>
; __device__ __forceinline__ void gemm_phase(LAS unsigned char* lds, const Gemm g, const StaticOrder& S, const Epi& E, int stagger_us, int tid_in) {
;     ...
;             const bool last = (t == nt - 2);
;             const char* a1 = cA + (size_t)(t + 1) * kstep;
;             const char* a2 = last ? nA : cA + (size_t)(t + 2) * kstep; const char* b2 = last ? nB : cB + (size_t)(t + 2) * kstep;
;             const char* a3 = a2 + kstep; const char* b3 = b2 + kstep;
;             PG8_LDB(B0, 0, 0); PG8_LDB(B1, 0, 1); PG8_SCHED; PG8_LDA(At, 0, 0); PG8_STAGE(PG8_SA(1, 1), a1 + hstepA, voffA);
;             PG8_WAIT_V(8); PG8_WAIT_L(0); PG8_BAR; PG8_MMA(0, 0, At, B0); PG8_MMA(0, 1, At, B1); PG8_BAR; PG8_SCHED;
;             PG8_LDA(At, 0, 1); PG8_STAGE(PG8_SB(0, 0), b2, voffB); PG8_STAGE(PG8_SB(0, 1), b2 + hstepB, voffB); PG8_STAGE(PG8_SA(0, 0), a2, voffA);
.LBB0_396:
	s_add_u32 s4, s60, 0xfff80080
	s_addc_u32 s5, s61, -1
	s_add_i32 s30, 0, 0x10000
	s_cmp_eq_u32 s29, 28
	s_cselect_b32 s7, s27, s5
	s_cselect_b32 s6, s28, s4
	v_add_u32_e32 v140, s30, v162
	s_cselect_b32 s5, s49, vcc_hi
	s_cselect_b32 s4, s51, vcc_lo
	s_add_i32 s44, 0, 0x14000
	ds_read_b128 v[144:147], v140
	ds_read_b128 v[148:151], v140 offset:1024
	ds_read_b128 v[152:155], v140 offset:2048
	ds_read_b128 v[156:159], v140 offset:3072
	v_add_u32_e32 v140, s44, v162
	ds_read_b128 v[166:169], v140
	ds_read_b128 v[170:173], v140 offset:1024
	ds_read_b128 v[174:177], v140 offset:2048
	ds_read_b128 v[178:181], v140 offset:3072
	v_lshl_add_u64 v[140:141], s[60:61], 0, v[136:137]
	s_add_i32 m0, s57, 0xc000
	ds_read_b128 v[182:185], v164
	ds_read_b128 v[186:189], v164 offset:1024
	ds_read_b128 v[190:193], v164 offset:2048
	ds_read_b128 v[194:197], v164 offset:3072
	ds_read_b128 v[198:201], v164 offset:4096
	ds_read_b128 v[202:205], v164 offset:5120
	ds_read_b128 v[206:209], v164 offset:6144
	ds_read_b128 v[210:213], v164 offset:7168
	global_load_lds_dwordx4 v[140:141], off
	s_add_i32 m0, s57, 0xe000
	v_lshl_add_u64 v[140:141], s[60:61], 0, v[138:139]
	global_load_lds_dwordx4 v[140:141], off
	s_setprio 1
	s_waitcnt vmcnt(8) lgkmcnt(0)
	s_barrier
	v_mfma_f32_16x16x32_bf16 v[126:129], v[144:147], v[182:185], v[126:129]
	v_mfma_f32_16x16x32_bf16 v[122:125], v[152:155], v[182:185], v[122:125]
	v_mfma_f32_16x16x32_bf16 v[110:113], v[144:147], v[190:193], v[110:113]
	v_mfma_f32_16x16x32_bf16 v[106:109], v[152:155], v[190:193], v[106:109]
	v_mfma_f32_16x16x32_bf16 v[94:97], v[144:147], v[198:201], v[94:97]
	v_mfma_f32_16x16x32_bf16 v[90:93], v[152:155], v[198:201], v[90:93]
	v_mfma_f32_16x16x32_bf16 v[78:81], v[144:147], v[206:209], v[78:81]
	v_mfma_f32_16x16x32_bf16 v[74:77], v[152:155], v[206:209], v[74:77]
	v_mfma_f32_16x16x32_bf16 v[126:129], v[148:151], v[186:189], v[126:129]
	v_mfma_f32_16x16x32_bf16 v[122:125], v[156:159], v[186:189], v[122:125]
	v_mfma_f32_16x16x32_bf16 v[110:113], v[148:151], v[194:197], v[110:113]
	v_mfma_f32_16x16x32_bf16 v[106:109], v[156:159], v[194:197], v[106:109]
	v_mfma_f32_16x16x32_bf16 v[94:97], v[148:151], v[202:205], v[94:97]
	v_mfma_f32_16x16x32_bf16 v[90:93], v[156:159], v[202:205], v[90:93]
	v_mfma_f32_16x16x32_bf16 v[78:81], v[148:151], v[210:213], v[78:81]
	v_mfma_f32_16x16x32_bf16 v[74:77], v[156:159], v[210:213], v[74:77]
	v_mfma_f32_16x16x32_bf16 v[118:121], v[166:169], v[182:185], v[118:121]
	v_mfma_f32_16x16x32_bf16 v[114:117], v[174:177], v[182:185], v[114:117]
	v_mfma_f32_16x16x32_bf16 v[102:105], v[166:169], v[190:193], v[102:105]
	v_mfma_f32_16x16x32_bf16 v[98:101], v[174:177], v[190:193], v[98:101]
	v_mfma_f32_16x16x32_bf16 v[86:89], v[166:169], v[198:201], v[86:89]
	v_mfma_f32_16x16x32_bf16 v[82:85], v[174:177], v[198:201], v[82:85]
	v_mfma_f32_16x16x32_bf16 v[70:73], v[166:169], v[206:209], v[70:73]
	v_mfma_f32_16x16x32_bf16 v[66:69], v[174:177], v[206:209], v[66:69]
	v_mfma_f32_16x16x32_bf16 v[118:121], v[170:173], v[186:189], v[118:121]
	v_mfma_f32_16x16x32_bf16 v[114:117], v[178:181], v[186:189], v[114:117]
	v_mfma_f32_16x16x32_bf16 v[102:105], v[170:173], v[194:197], v[102:105]
	v_mfma_f32_16x16x32_bf16 v[98:101], v[178:181], v[194:197], v[98:101]
	v_mfma_f32_16x16x32_bf16 v[86:89], v[170:173], v[202:205], v[86:89]
	v_mfma_f32_16x16x32_bf16 v[82:85], v[178:181], v[202:205], v[82:85]
	v_mfma_f32_16x16x32_bf16 v[70:73], v[170:173], v[210:213], v[70:73]
	s_setprio 0
	v_mfma_f32_16x16x32_bf16 v[66:69], v[178:181], v[210:213], v[66:69]
	s_barrier
	s_add_i32 s30, s30, s66
	v_lshl_add_u64 v[140:141], s[4:5], 0, v[0:1]
	s_mov_b32 m0, s30
	ds_read_b128 v[182:185], v164 offset:16384
	ds_read_b128 v[186:189], v164 offset:17408
	ds_read_b128 v[190:193], v164 offset:18432
	ds_read_b128 v[194:197], v164 offset:19456
	ds_read_b128 v[198:201], v164 offset:20480
	ds_read_b128 v[202:205], v164 offset:21504
	ds_read_b128 v[206:209], v164 offset:22528
	ds_read_b128 v[210:213], v164 offset:23552
	global_load_lds_dwordx4 v[140:141], off
	s_add_i32 m0, s30, 0x2000
	s_add_u32 s30, s4, 0x80000
	v_lshl_add_u64 v[160:161], s[4:5], 0, v[130:131]
	s_addc_u32 s31, s5, 0
	s_add_i32 s44, s44, s66
	global_load_lds_dwordx4 v[160:161], off
	v_lshl_add_u64 v[214:215], s[30:31], 0, v[0:1]
	s_mov_b32 m0, s44
	v_lshl_add_u64 v[216:217], s[6:7], 0, v[132:133]
	global_load_lds_dwordx4 v[214:215], off
	s_add_i32 m0, s44, 0x2000
	v_lshl_add_u64 v[214:215], s[30:31], 0, v[130:131]
	global_load_lds_dwordx4 v[214:215], off
	s_mov_b32 m0, s57
	v_lshl_add_u64 v[214:215], s[6:7], 0, v[134:135]
	global_load_lds_dwordx4 v[214:215], off
	s_mov_b32 m0, s59
	s_nop 0
	global_load_lds_dwordx4 v[216:217], off
	s_setprio 1
	s_waitcnt vmcnt(8) lgkmcnt(0)
	s_barrier
; #define PG8_STAGE(bufoff, gbase, voff) do { _Pragma("unroll") for (int _i = 0; _i < 2; ++_i) \
;         __builtin_amdgcn_global_load_lds((const unsigned*)((const char*)(gbase) + (voff)[_i]), (LAS unsigned*)(lds + (bufoff) + ldsw + _i * 8192), 16, 0, 0); } while (0)
; #define PG8_LDA(dst, b, h) do { _Pragma("unroll") for (int m = 0; m < 4; ++m) _Pragma("unroll") for (int k = 0; k < 2; ++k) dst[m][k] = *(const LAS bf16x8*)(lds + PG8_SA(b, h) + aoff + m * 2048 + k * 1024); } while (0)
; #define PG8_LDB(dst, b, h) do { _Pragma("unroll") for (int n = 0; n < 2; ++n) _Pragma("unroll") for (int k = 0; k < 2; ++k) dst[n][k] = *(const LAS bf16x8*)(lds + PG8_SB(b, h) + boff + n * 2048 + k * 1024); } while (0)
; #define PG8_MMA(ai, bj, At, Bt) do { __builtin_amdgcn_s_setprio(1); _Pragma("unroll") for (int m = 0; m < 4; ++m) _Pragma("unroll") for (int n = 0; n < 2; ++n) _Pragma("unroll") for (int k = 0; k < 2; ++k) \
;         acc[ai][bj][m][n] = __builtin_amdgcn_mfma_f32_16x16x32_bf16(Bt[n][k], At[m][k], acc[ai][bj][m][n], 0, 0, 0); __builtin_amdgcn_s_setprio(0); } while (0)
; #define PG8_WAIT_V(n) asm volatile("s_waitcnt vmcnt(" #n ")" ::: "memory")
; #define PG8_WAIT_L(n) asm volatile("s_waitcnt lgkmcnt(" #n ")" ::: "memory")
; #define PG8_BAR __builtin_amdgcn_s_barrier()
; #define PG8_SCHED __builtin_amdgcn_sched_barrier(0)
; template <class Epi, int AMODE>
; __device__ __forceinline__ void gemm_phase(LAS unsigned char* lds, const Gemm g, const StaticOrder& S, const Epi& E, int stagger_us, int tid_in) {
;     ...
;             PG8_WAIT_V(8); PG8_WAIT_L(0); PG8_BAR; PG8_MMA(1, 0, At, B0); PG8_MMA(1, 1, At, B1); PG8_BAR; PG8_SCHED;
;             PG8_LDB(B0, 1, 0); PG8_LDB(B1, 1, 1); PG8_SCHED; PG8_LDA(At, 1, 0); PG8_STAGE(PG8_SA(0, 1), a2 + hstepA, voffA);
;             PG8_WAIT_V(8); PG8_WAIT_L(0); PG8_BAR; PG8_MMA(0, 0, At, B0); PG8_MMA(0, 1, At, B1); PG8_BAR; PG8_SCHED;
	v_mfma_f32_16x16x32_bf16 v[62:65], v[144:147], v[182:185], v[62:65]
	v_mfma_f32_16x16x32_bf16 v[58:61], v[152:155], v[182:185], v[58:61]
	v_mfma_f32_16x16x32_bf16 v[46:49], v[144:147], v[190:193], v[46:49]
	v_mfma_f32_16x16x32_bf16 v[42:45], v[152:155], v[190:193], v[42:45]
	v_mfma_f32_16x16x32_bf16 v[30:33], v[144:147], v[198:201], v[30:33]
	v_mfma_f32_16x16x32_bf16 v[26:29], v[152:155], v[198:201], v[26:29]
	v_mfma_f32_16x16x32_bf16 v[14:17], v[144:147], v[206:209], v[14:17]
	v_mfma_f32_16x16x32_bf16 v[10:13], v[152:155], v[206:209], v[10:13]
	v_mfma_f32_16x16x32_bf16 v[62:65], v[148:151], v[186:189], v[62:65]
	v_mfma_f32_16x16x32_bf16 v[58:61], v[156:159], v[186:189], v[58:61]
	v_mfma_f32_16x16x32_bf16 v[46:49], v[148:151], v[194:197], v[46:49]
	v_mfma_f32_16x16x32_bf16 v[42:45], v[156:159], v[194:197], v[42:45]
	v_mfma_f32_16x16x32_bf16 v[30:33], v[148:151], v[202:205], v[30:33]
	v_mfma_f32_16x16x32_bf16 v[26:29], v[156:159], v[202:205], v[26:29]
	v_mfma_f32_16x16x32_bf16 v[14:17], v[148:151], v[210:213], v[14:17]
	v_mfma_f32_16x16x32_bf16 v[10:13], v[156:159], v[210:213], v[10:13]
	v_mfma_f32_16x16x32_bf16 v[54:57], v[166:169], v[182:185], v[54:57]
	v_mfma_f32_16x16x32_bf16 v[50:53], v[174:177], v[182:185], v[50:53]
	v_mfma_f32_16x16x32_bf16 v[38:41], v[166:169], v[190:193], v[38:41]
	v_mfma_f32_16x16x32_bf16 v[34:37], v[174:177], v[190:193], v[34:37]
	v_mfma_f32_16x16x32_bf16 v[22:25], v[166:169], v[198:201], v[22:25]
	v_mfma_f32_16x16x32_bf16 v[18:21], v[174:177], v[198:201], v[18:21]
	v_mfma_f32_16x16x32_bf16 v[6:9], v[166:169], v[206:209], v[6:9]
	v_mfma_f32_16x16x32_bf16 v[2:5], v[174:177], v[206:209], v[2:5]
	v_mfma_f32_16x16x32_bf16 v[54:57], v[170:173], v[186:189], v[54:57]
	v_mfma_f32_16x16x32_bf16 v[50:53], v[178:181], v[186:189], v[50:53]
	v_mfma_f32_16x16x32_bf16 v[38:41], v[170:173], v[194:197], v[38:41]
	v_mfma_f32_16x16x32_bf16 v[34:37], v[178:181], v[194:197], v[34:37]
	v_mfma_f32_16x16x32_bf16 v[22:25], v[170:173], v[202:205], v[22:25]
	v_mfma_f32_16x16x32_bf16 v[18:21], v[178:181], v[202:205], v[18:21]
	v_mfma_f32_16x16x32_bf16 v[6:9], v[170:173], v[210:213], v[6:9]
	s_setprio 0
	v_mfma_f32_16x16x32_bf16 v[2:5], v[178:181], v[210:213], v[2:5]
	s_barrier
	s_add_i32 s30, 0, 0x18000
	v_add_u32_e32 v142, s30, v162
	s_add_i32 s31, 0, 0x1c000
	ds_read_b128 v[144:147], v142
	ds_read_b128 v[148:151], v142 offset:1024
	ds_read_b128 v[152:155], v142 offset:2048
	ds_read_b128 v[156:159], v142 offset:3072
	v_add_u32_e32 v142, s31, v162
	ds_read_b128 v[166:169], v142
	ds_read_b128 v[170:173], v142 offset:1024
	ds_read_b128 v[174:177], v142 offset:2048
	ds_read_b128 v[178:181], v142 offset:3072
	s_add_u32 s6, s6, 0x80000
	s_addc_u32 s7, s7, 0
	s_mov_b32 m0, s87
	v_lshl_add_u64 v[218:219], s[6:7], 0, v[134:135]
	ds_read_b128 v[182:185], v164 offset:32768
	ds_read_b128 v[186:189], v164 offset:33792
	ds_read_b128 v[190:193], v164 offset:34816
	ds_read_b128 v[194:197], v164 offset:35840
	ds_read_b128 v[198:201], v164 offset:36864
	ds_read_b128 v[202:205], v164 offset:37888
	ds_read_b128 v[206:209], v164 offset:38912
	ds_read_b128 v[210:213], v164 offset:39936
	global_load_lds_dwordx4 v[218:219], off
	s_mov_b32 m0, s91
	v_lshl_add_u64 v[218:219], s[6:7], 0, v[132:133]
	global_load_lds_dwordx4 v[218:219], off
	s_setprio 1
	s_waitcnt vmcnt(8) lgkmcnt(0)
	s_barrier
	v_mfma_f32_16x16x32_bf16 v[126:129], v[144:147], v[182:185], v[126:129]
	v_mfma_f32_16x16x32_bf16 v[122:125], v[152:155], v[182:185], v[122:125]
	v_mfma_f32_16x16x32_bf16 v[110:113], v[144:147], v[190:193], v[110:113]
	v_mfma_f32_16x16x32_bf16 v[106:109], v[152:155], v[190:193], v[106:109]
	v_mfma_f32_16x16x32_bf16 v[94:97], v[144:147], v[198:201], v[94:97]
	v_mfma_f32_16x16x32_bf16 v[90:93], v[152:155], v[198:201], v[90:93]
	v_mfma_f32_16x16x32_bf16 v[78:81], v[144:147], v[206:209], v[78:81]
	v_mfma_f32_16x16x32_bf16 v[74:77], v[152:155], v[206:209], v[74:77]
	v_mfma_f32_16x16x32_bf16 v[126:129], v[148:151], v[186:189], v[126:129]
	v_mfma_f32_16x16x32_bf16 v[122:125], v[156:159], v[186:189], v[122:125]
	v_mfma_f32_16x16x32_bf16 v[110:113], v[148:151], v[194:197], v[110:113]
	v_mfma_f32_16x16x32_bf16 v[106:109], v[156:159], v[194:197], v[106:109]
	v_mfma_f32_16x16x32_bf16 v[94:97], v[148:151], v[202:205], v[94:97]
	v_mfma_f32_16x16x32_bf16 v[90:93], v[156:159], v[202:205], v[90:93]
	v_mfma_f32_16x16x32_bf16 v[78:81], v[148:151], v[210:213], v[78:81]
	v_mfma_f32_16x16x32_bf16 v[74:77], v[156:159], v[210:213], v[74:77]
	v_mfma_f32_16x16x32_bf16 v[118:121], v[166:169], v[182:185], v[118:121]
	v_mfma_f32_16x16x32_bf16 v[114:117], v[174:177], v[182:185], v[114:117]
	v_mfma_f32_16x16x32_bf16 v[102:105], v[166:169], v[190:193], v[102:105]
	v_mfma_f32_16x16x32_bf16 v[98:101], v[174:177], v[190:193], v[98:101]
	v_mfma_f32_16x16x32_bf16 v[86:89], v[166:169], v[198:201], v[86:89]
	v_mfma_f32_16x16x32_bf16 v[82:85], v[174:177], v[198:201], v[82:85]
	v_mfma_f32_16x16x32_bf16 v[70:73], v[166:169], v[206:209], v[70:73]
	v_mfma_f32_16x16x32_bf16 v[66:69], v[174:177], v[206:209], v[66:69]
	v_mfma_f32_16x16x32_bf16 v[118:121], v[170:173], v[186:189], v[118:121]
	v_mfma_f32_16x16x32_bf16 v[114:117], v[178:181], v[186:189], v[114:117]
	v_mfma_f32_16x16x32_bf16 v[102:105], v[170:173], v[194:197], v[102:105]
	v_mfma_f32_16x16x32_bf16 v[98:101], v[178:181], v[194:197], v[98:101]
	v_mfma_f32_16x16x32_bf16 v[86:89], v[170:173], v[202:205], v[86:89]
	v_mfma_f32_16x16x32_bf16 v[82:85], v[178:181], v[202:205], v[82:85]
	v_mfma_f32_16x16x32_bf16 v[70:73], v[170:173], v[210:213], v[70:73]
	s_setprio 0
	v_mfma_f32_16x16x32_bf16 v[66:69], v[178:181], v[210:213], v[66:69]
	s_barrier
; #define PG8_STAGE(bufoff, gbase, voff) do { _Pragma("unroll") for (int _i = 0; _i < 2; ++_i) \
;         __builtin_amdgcn_global_load_lds((const unsigned*)((const char*)(gbase) + (voff)[_i]), (LAS unsigned*)(lds + (bufoff) + ldsw + _i * 8192), 16, 0, 0); } while (0)
; #define PG8_LDA(dst, b, h) do { _Pragma("unroll") for (int m = 0; m < 4; ++m) _Pragma("unroll") for (int k = 0; k < 2; ++k) dst[m][k] = *(const LAS bf16x8*)(lds + PG8_SA(b, h) + aoff + m * 2048 + k * 1024); } while (0)
; #define PG8_MMA(ai, bj, At, Bt) do { __builtin_amdgcn_s_setprio(1); _Pragma("unroll") for (int m = 0; m < 4; ++m) _Pragma("unroll") for (int n = 0; n < 2; ++n) _Pragma("unroll") for (int k = 0; k < 2; ++k) \
;         acc[ai][bj][m][n] = __builtin_amdgcn_mfma_f32_16x16x32_bf16(Bt[n][k], At[m][k], acc[ai][bj][m][n], 0, 0, 0); __builtin_amdgcn_s_setprio(0); } while (0)
; #define PG8_WAIT_V(n) asm volatile("s_waitcnt vmcnt(" #n ")" ::: "memory")
; #define PG8_WAIT_L(n) asm volatile("s_waitcnt lgkmcnt(" #n ")" ::: "memory")
; #define PG8_BAR __builtin_amdgcn_s_barrier()
; #define PG8_SCHED __builtin_amdgcn_sched_barrier(0)
; template <class Epi, int AMODE>
; __device__ __forceinline__ void gemm_phase(LAS unsigned char* lds, const Gemm g, const StaticOrder& S, const Epi& E, int stagger_us, int tid_in) {
;     ...
;             PG8_LDA(At, 1, 1); PG8_STAGE(PG8_SB(1, 0), b3, voffB); PG8_STAGE(PG8_SB(1, 1), b3 + hstepB, voffB); PG8_STAGE(PG8_SA(1, 0), a3, voffA);
;             PG8_WAIT_V(8); PG8_WAIT_L(0); PG8_BAR; PG8_MMA(1, 0, At, B0); PG8_MMA(1, 1, At, B1); PG8_BAR; PG8_SCHED;
;         }
;         if (wr == 0) PG8_BAR;
	s_add_i32 s6, s30, s66
	v_lshl_add_u64 v[140:141], v[140:141], 0, s[74:75]
	s_mov_b32 m0, s6
	ds_read_b128 v[182:185], v164 offset:49152
	ds_read_b128 v[186:189], v164 offset:50176
	ds_read_b128 v[190:193], v164 offset:51200
	ds_read_b128 v[194:197], v164 offset:52224
	ds_read_b128 v[198:201], v164 offset:53248
	ds_read_b128 v[202:205], v164 offset:54272
	ds_read_b128 v[206:209], v164 offset:55296
	ds_read_b128 v[210:213], v164 offset:56320
	global_load_lds_dwordx4 v[140:141], off
	s_add_i32 m0, s6, 0x2000
	s_add_u32 s4, s4, 0x80080
	v_lshl_add_u64 v[140:141], v[160:161], 0, s[74:75]
	s_addc_u32 s5, s5, 0
	s_add_i32 s6, s31, s66
	global_load_lds_dwordx4 v[140:141], off
	s_mov_b32 m0, s6
	v_lshl_add_u64 v[140:141], s[4:5], 0, v[0:1]
	global_load_lds_dwordx4 v[140:141], off
	s_add_i32 m0, s6, 0x2000
	v_lshl_add_u64 v[140:141], s[4:5], 0, v[130:131]
	global_load_lds_dwordx4 v[140:141], off
	s_mov_b32 m0, s95
	v_lshl_add_u64 v[140:141], v[214:215], 0, s[74:75]
	global_load_lds_dwordx4 v[140:141], off
	s_mov_b32 m0, s96
	v_lshl_add_u64 v[140:141], v[216:217], 0, s[74:75]
	global_load_lds_dwordx4 v[140:141], off
	s_setprio 1
	s_waitcnt vmcnt(8) lgkmcnt(0)
	s_barrier
	v_mfma_f32_16x16x32_bf16 v[62:65], v[144:147], v[182:185], v[62:65]
	v_mfma_f32_16x16x32_bf16 v[58:61], v[152:155], v[182:185], v[58:61]
	v_mfma_f32_16x16x32_bf16 v[46:49], v[144:147], v[190:193], v[46:49]
	v_mfma_f32_16x16x32_bf16 v[42:45], v[152:155], v[190:193], v[42:45]
	v_mfma_f32_16x16x32_bf16 v[30:33], v[144:147], v[198:201], v[30:33]
	v_mfma_f32_16x16x32_bf16 v[26:29], v[152:155], v[198:201], v[26:29]
	v_mfma_f32_16x16x32_bf16 v[14:17], v[144:147], v[206:209], v[14:17]
	v_mfma_f32_16x16x32_bf16 v[10:13], v[152:155], v[206:209], v[10:13]
	v_mfma_f32_16x16x32_bf16 v[62:65], v[148:151], v[186:189], v[62:65]
	v_mfma_f32_16x16x32_bf16 v[58:61], v[156:159], v[186:189], v[58:61]
	v_mfma_f32_16x16x32_bf16 v[46:49], v[148:151], v[194:197], v[46:49]
	v_mfma_f32_16x16x32_bf16 v[42:45], v[156:159], v[194:197], v[42:45]
	v_mfma_f32_16x16x32_bf16 v[30:33], v[148:151], v[202:205], v[30:33]
	v_mfma_f32_16x16x32_bf16 v[26:29], v[156:159], v[202:205], v[26:29]
	v_mfma_f32_16x16x32_bf16 v[14:17], v[148:151], v[210:213], v[14:17]
	v_mfma_f32_16x16x32_bf16 v[10:13], v[156:159], v[210:213], v[10:13]
	v_mfma_f32_16x16x32_bf16 v[54:57], v[166:169], v[182:185], v[54:57]
	v_mfma_f32_16x16x32_bf16 v[50:53], v[174:177], v[182:185], v[50:53]
	v_mfma_f32_16x16x32_bf16 v[38:41], v[166:169], v[190:193], v[38:41]
	v_mfma_f32_16x16x32_bf16 v[34:37], v[174:177], v[190:193], v[34:37]
	v_mfma_f32_16x16x32_bf16 v[22:25], v[166:169], v[198:201], v[22:25]
	v_mfma_f32_16x16x32_bf16 v[18:21], v[174:177], v[198:201], v[18:21]
	v_mfma_f32_16x16x32_bf16 v[6:9], v[166:169], v[206:209], v[6:9]
	v_mfma_f32_16x16x32_bf16 v[2:5], v[174:177], v[206:209], v[2:5]
	v_mfma_f32_16x16x32_bf16 v[54:57], v[170:173], v[186:189], v[54:57]
	v_mfma_f32_16x16x32_bf16 v[50:53], v[178:181], v[186:189], v[50:53]
	v_mfma_f32_16x16x32_bf16 v[38:41], v[170:173], v[194:197], v[38:41]
	v_mfma_f32_16x16x32_bf16 v[34:37], v[178:181], v[194:197], v[34:37]
	v_mfma_f32_16x16x32_bf16 v[22:25], v[170:173], v[202:205], v[22:25]
	v_mfma_f32_16x16x32_bf16 v[18:21], v[178:181], v[202:205], v[18:21]
	v_mfma_f32_16x16x32_bf16 v[6:9], v[170:173], v[210:213], v[6:9]
	s_setprio 0
	v_mfma_f32_16x16x32_bf16 v[2:5], v[178:181], v[210:213], v[2:5]
	s_barrier
	s_add_i32 s29, s29, 2
	s_add_u32 s60, s60, 0x100
	s_addc_u32 s61, s61, 0
	s_add_u32 vcc_lo, vcc_lo, 0x100
	s_addc_u32 vcc_hi, vcc_hi, 0
	s_cmp_gt_u32 s29, 29
	s_cbranch_scc0 .LBB0_396
	s_and_b64 vcc, exec, s[46:47]
	s_cbranch_vccz .LBB0_399
	s_barrier

; #define PG8_STAGE(bufoff, gbase, voff) do { _Pragma("unroll") for (int _i = 0; _i < 2; ++_i) \
;         __builtin_amdgcn_global_load_lds((const unsigned*)((const char*)(gbase) + (voff)[_i]), (LAS unsigned*)(lds + (bufoff) + ldsw + _i * 8192), 16, 0, 0); } while (0)
; #define PG8_LDA(dst, b, h) do { _Pragma("unroll") for (int m = 0; m < 4; ++m) _Pragma("unroll") for (int k = 0; k < 2; ++k) dst[m][k] = *(const LAS bf16x8*)(lds + PG8_SA(b, h) + aoff + m * 2048 + k * 1024); } while (0)
; #define PG8_LDB(dst, b, h) do { _Pragma("unroll") for (int n = 0; n < 2; ++n) _Pragma("unroll") for (int k = 0; k < 2; ++k) dst[n][k] = *(const LAS bf16x8*)(lds + PG8_SB(b, h) + boff + n * 2048 + k * 1024); } while (0)
; #define PG8_MMA(ai, bj, At, Bt) do { __builtin_amdgcn_s_setprio(1); _Pragma("unroll") for (int m = 0; m < 4; ++m) _Pragma("unroll") for (int n = 0; n < 2; ++n) _Pragma("unroll") for (int k = 0; k < 2; ++k) \
;         acc[ai][bj][m][n] = __builtin_amdgcn_mfma_f32_16x16x32_bf16(Bt[n][k], At[m][k], acc[ai][bj][m][n], 0, 0, 0); __builtin_amdgcn_s_setprio(0); } while (0)
; #define PG8_WAIT_V(n) asm volatile("s_waitcnt vmcnt(" #n ")" ::: "memory")
; #define PG8_WAIT_L(n) asm volatile("s_waitcnt lgkmcnt(" #n ")" ::: "memory")
; #define PG8_BAR __builtin_amdgcn_s_barrier()
; #define PG8_SCHED __builtin_amdgcn_sched_barrier(0)
; template <class Epi, int AMODE>
; __device__ __forceinline__ void gemm_phase(LAS unsigned char* lds, const Gemm g, const StaticOrder& S, const Epi& E, int stagger_us, int tid_in) {
;     ...
;             const bool last = (t == nt - 2);
;             const char* a1 = cA + (size_t)(t + 1) * kstep;
;             const char* a2 = last ? nA : cA + (size_t)(t + 2) * kstep; const char* b2 = last ? nB : cB + (size_t)(t + 2) * kstep;
;             const char* a3 = a2 + kstep; const char* b3 = b2 + kstep;
;             PG8_LDB(B0, 0, 0); PG8_LDB(B1, 0, 1); PG8_SCHED; PG8_LDA(At, 0, 0); PG8_STAGE(PG8_SA(1, 1), a1 + hstepA, voffA);
;             PG8_WAIT_V(8); PG8_WAIT_L(0); PG8_BAR; PG8_MMA(0, 0, At, B0); PG8_MMA(0, 1, At, B1); PG8_BAR; PG8_SCHED;
;             PG8_LDA(At, 0, 1); PG8_STAGE(PG8_SB(0, 0), b2, voffB); PG8_STAGE(PG8_SB(0, 1), b2 + hstepB, voffB); PG8_STAGE(PG8_SA(0, 0), a2, voffA);
.LBB0_1199:
	s_add_u32 s4, s46, 0x100
	s_addc_u32 s5, s47, 0
	s_add_i32 s34, 0, 0x10000
	s_cmp_eq_u32 s31, 28
	s_cselect_b32 s95, s61, s5
	s_cselect_b32 s94, vcc_lo, s4
	s_cselect_b32 s7, s59, s30
	s_cselect_b32 s6, vcc_hi, s29
	s_add_i32 s35, 0, 0x14000
	v_add_u32_e32 v62, s34, v205
	v_add_u32_e32 v158, s35, v205
	ds_read_b128 v[50:53], v62
	ds_read_b128 v[54:57], v62 offset:1024
	ds_read_b128 v[58:61], v62 offset:2048
	ds_read_b128 v[62:65], v62 offset:3072
	ds_read_b128 v[146:149], v158
	ds_read_b128 v[150:153], v158 offset:1024
	ds_read_b128 v[154:157], v158 offset:2048
	ds_read_b128 v[158:161], v158 offset:3072
	v_lshl_add_u64 v[200:201], s[46:47], 0, v[176:177]
	s_add_i32 m0, s66, 0xc000
	ds_read_b128 v[162:165], v207
	ds_read_b128 v[166:169], v207 offset:1024
	ds_read_b128 v[170:173], v207 offset:2048
	ds_read_b128 v[180:183], v207 offset:3072
	ds_read_b128 v[184:187], v207 offset:4096
	ds_read_b128 v[188:191], v207 offset:5120
	ds_read_b128 v[192:195], v207 offset:6144
	ds_read_b128 v[196:199], v207 offset:7168
	global_load_lds_dwordx4 v[200:201], off
	s_add_i32 m0, s66, 0xe000
	v_lshl_add_u64 v[200:201], s[46:47], 0, v[178:179]
	global_load_lds_dwordx4 v[200:201], off
	s_setprio 1
	s_waitcnt vmcnt(8) lgkmcnt(0)
	s_barrier
	v_mfma_f32_16x16x32_bf16 v[142:145], v[50:53], v[162:165], v[142:145]
	v_mfma_f32_16x16x32_bf16 v[138:141], v[58:61], v[162:165], v[138:141]
	v_mfma_f32_16x16x32_bf16 v[126:129], v[50:53], v[170:173], v[126:129]
	v_mfma_f32_16x16x32_bf16 v[122:125], v[58:61], v[170:173], v[122:125]
	v_mfma_f32_16x16x32_bf16 v[110:113], v[50:53], v[184:187], v[110:113]
	v_mfma_f32_16x16x32_bf16 v[106:109], v[58:61], v[184:187], v[106:109]
	v_mfma_f32_16x16x32_bf16 v[94:97], v[50:53], v[192:195], v[94:97]
	v_mfma_f32_16x16x32_bf16 v[90:93], v[58:61], v[192:195], v[90:93]
	v_mfma_f32_16x16x32_bf16 v[142:145], v[54:57], v[166:169], v[142:145]
	v_mfma_f32_16x16x32_bf16 v[138:141], v[62:65], v[166:169], v[138:141]
	v_mfma_f32_16x16x32_bf16 v[126:129], v[54:57], v[180:183], v[126:129]
	v_mfma_f32_16x16x32_bf16 v[122:125], v[62:65], v[180:183], v[122:125]
	v_mfma_f32_16x16x32_bf16 v[110:113], v[54:57], v[188:191], v[110:113]
	v_mfma_f32_16x16x32_bf16 v[106:109], v[62:65], v[188:191], v[106:109]
	v_mfma_f32_16x16x32_bf16 v[94:97], v[54:57], v[196:199], v[94:97]
	v_mfma_f32_16x16x32_bf16 v[90:93], v[62:65], v[196:199], v[90:93]
	v_mfma_f32_16x16x32_bf16 v[134:137], v[146:149], v[162:165], v[134:137]
	v_mfma_f32_16x16x32_bf16 v[130:133], v[154:157], v[162:165], v[130:133]
	v_mfma_f32_16x16x32_bf16 v[118:121], v[146:149], v[170:173], v[118:121]
	v_mfma_f32_16x16x32_bf16 v[114:117], v[154:157], v[170:173], v[114:117]
	v_mfma_f32_16x16x32_bf16 v[102:105], v[146:149], v[184:187], v[102:105]
	v_mfma_f32_16x16x32_bf16 v[98:101], v[154:157], v[184:187], v[98:101]
	v_mfma_f32_16x16x32_bf16 v[86:89], v[146:149], v[192:195], v[86:89]
	v_mfma_f32_16x16x32_bf16 v[82:85], v[154:157], v[192:195], v[82:85]
	v_mfma_f32_16x16x32_bf16 v[134:137], v[150:153], v[166:169], v[134:137]
	v_mfma_f32_16x16x32_bf16 v[130:133], v[158:161], v[166:169], v[130:133]
	v_mfma_f32_16x16x32_bf16 v[118:121], v[150:153], v[180:183], v[118:121]
	v_mfma_f32_16x16x32_bf16 v[114:117], v[158:161], v[180:183], v[114:117]
	v_mfma_f32_16x16x32_bf16 v[102:105], v[150:153], v[188:191], v[102:105]
	v_mfma_f32_16x16x32_bf16 v[98:101], v[158:161], v[188:191], v[98:101]
	v_mfma_f32_16x16x32_bf16 v[86:89], v[150:153], v[196:199], v[86:89]
	s_setprio 0
	v_mfma_f32_16x16x32_bf16 v[82:85], v[158:161], v[196:199], v[82:85]
	s_barrier
	s_add_i32 s34, s34, s13
	v_lshl_add_u64 v[200:201], s[6:7], 0, v[0:1]
	s_mov_b32 m0, s34
	ds_read_b128 v[162:165], v207 offset:16384
	ds_read_b128 v[166:169], v207 offset:17408
	ds_read_b128 v[170:173], v207 offset:18432
	ds_read_b128 v[180:183], v207 offset:19456
	ds_read_b128 v[184:187], v207 offset:20480
	ds_read_b128 v[188:191], v207 offset:21504
	ds_read_b128 v[192:195], v207 offset:22528
	ds_read_b128 v[196:199], v207 offset:23552
	global_load_lds_dwordx4 v[200:201], off
	s_add_i32 m0, s34, 0x2000
	s_add_u32 s46, s6, 0x80000
	v_lshl_add_u64 v[202:203], s[6:7], 0, v[174:175]
	s_addc_u32 s47, s7, 0
	s_add_i32 s34, s35, s13
	global_load_lds_dwordx4 v[202:203], off
	v_lshl_add_u64 v[208:209], s[46:47], 0, v[0:1]
	s_mov_b32 m0, s34
	v_lshl_add_u64 v[210:211], s[94:95], 0, v[174:175]
	global_load_lds_dwordx4 v[208:209], off
	s_add_i32 m0, s34, 0x2000
	v_lshl_add_u64 v[208:209], s[46:47], 0, v[174:175]
	global_load_lds_dwordx4 v[208:209], off
	s_mov_b32 m0, s66
	v_lshl_add_u64 v[208:209], s[94:95], 0, v[0:1]
	global_load_lds_dwordx4 v[208:209], off
	s_mov_b32 m0, s67
	s_nop 0
	global_load_lds_dwordx4 v[210:211], off
	s_setprio 1
	s_waitcnt vmcnt(8) lgkmcnt(0)
	s_barrier
; #define PG8_STAGE(bufoff, gbase, voff) do { _Pragma("unroll") for (int _i = 0; _i < 2; ++_i) \
;         __builtin_amdgcn_global_load_lds((const unsigned*)((const char*)(gbase) + (voff)[_i]), (LAS unsigned*)(lds + (bufoff) + ldsw + _i * 8192), 16, 0, 0); } while (0)
; #define PG8_LDA(dst, b, h) do { _Pragma("unroll") for (int m = 0; m < 4; ++m) _Pragma("unroll") for (int k = 0; k < 2; ++k) dst[m][k] = *(const LAS bf16x8*)(lds + PG8_SA(b, h) + aoff + m * 2048 + k * 1024); } while (0)
; #define PG8_LDB(dst, b, h) do { _Pragma("unroll") for (int n = 0; n < 2; ++n) _Pragma("unroll") for (int k = 0; k < 2; ++k) dst[n][k] = *(const LAS bf16x8*)(lds + PG8_SB(b, h) + boff + n * 2048 + k * 1024); } while (0)
; #define PG8_MMA(ai, bj, At, Bt) do { __builtin_amdgcn_s_setprio(1); _Pragma("unroll") for (int m = 0; m < 4; ++m) _Pragma("unroll") for (int n = 0; n < 2; ++n) _Pragma("unroll") for (int k = 0; k < 2; ++k) \
;         acc[ai][bj][m][n] = __builtin_amdgcn_mfma_f32_16x16x32_bf16(Bt[n][k], At[m][k], acc[ai][bj][m][n], 0, 0, 0); __builtin_amdgcn_s_setprio(0); } while (0)
; #define PG8_WAIT_V(n) asm volatile("s_waitcnt vmcnt(" #n ")" ::: "memory")
; #define PG8_WAIT_L(n) asm volatile("s_waitcnt lgkmcnt(" #n ")" ::: "memory")
; #define PG8_BAR __builtin_amdgcn_s_barrier()
; #define PG8_SCHED __builtin_amdgcn_sched_barrier(0)
; template <class Epi, int AMODE>
; __device__ __forceinline__ void gemm_phase(LAS unsigned char* lds, const Gemm g, const StaticOrder& S, const Epi& E, int stagger_us, int tid_in) {
;     ...
;             PG8_WAIT_V(8); PG8_WAIT_L(0); PG8_BAR; PG8_MMA(1, 0, At, B0); PG8_MMA(1, 1, At, B1); PG8_BAR; PG8_SCHED;
;             PG8_LDB(B0, 1, 0); PG8_LDB(B1, 1, 1); PG8_SCHED; PG8_LDA(At, 1, 0); PG8_STAGE(PG8_SA(0, 1), a2 + hstepA, voffA);
;             PG8_WAIT_V(8); PG8_WAIT_L(0); PG8_BAR; PG8_MMA(0, 0, At, B0); PG8_MMA(0, 1, At, B1); PG8_BAR; PG8_SCHED;
	v_mfma_f32_16x16x32_bf16 v[78:81], v[50:53], v[162:165], v[78:81]
	v_mfma_f32_16x16x32_bf16 v[74:77], v[58:61], v[162:165], v[74:77]
	v_mfma_f32_16x16x32_bf16 v[46:49], v[50:53], v[170:173], v[46:49]
	v_mfma_f32_16x16x32_bf16 v[42:45], v[58:61], v[170:173], v[42:45]
	v_mfma_f32_16x16x32_bf16 v[30:33], v[50:53], v[184:187], v[30:33]
	v_mfma_f32_16x16x32_bf16 v[26:29], v[58:61], v[184:187], v[26:29]
	v_mfma_f32_16x16x32_bf16 v[14:17], v[50:53], v[192:195], v[14:17]
	v_mfma_f32_16x16x32_bf16 v[10:13], v[58:61], v[192:195], v[10:13]
	v_mfma_f32_16x16x32_bf16 v[78:81], v[54:57], v[166:169], v[78:81]
	v_mfma_f32_16x16x32_bf16 v[74:77], v[62:65], v[166:169], v[74:77]
	v_mfma_f32_16x16x32_bf16 v[46:49], v[54:57], v[180:183], v[46:49]
	v_mfma_f32_16x16x32_bf16 v[42:45], v[62:65], v[180:183], v[42:45]
	v_mfma_f32_16x16x32_bf16 v[30:33], v[54:57], v[188:191], v[30:33]
	v_mfma_f32_16x16x32_bf16 v[26:29], v[62:65], v[188:191], v[26:29]
	v_mfma_f32_16x16x32_bf16 v[14:17], v[54:57], v[196:199], v[14:17]
	v_mfma_f32_16x16x32_bf16 v[10:13], v[62:65], v[196:199], v[10:13]
	v_mfma_f32_16x16x32_bf16 v[38:41], v[146:149], v[170:173], v[38:41]
	v_mfma_f32_16x16x32_bf16 v[34:37], v[154:157], v[170:173], v[34:37]
	v_mfma_f32_16x16x32_bf16 v[22:25], v[146:149], v[184:187], v[22:25]
	v_mfma_f32_16x16x32_bf16 v[18:21], v[154:157], v[184:187], v[18:21]
	v_mfma_f32_16x16x32_bf16 v[6:9], v[146:149], v[192:195], v[6:9]
	v_mfma_f32_16x16x32_bf16 v[2:5], v[154:157], v[192:195], v[2:5]
	v_mfma_f32_16x16x32_bf16 v[50:53], v[146:149], v[162:165], v[70:73]
	v_mfma_f32_16x16x32_bf16 v[54:57], v[154:157], v[162:165], v[66:69]
	v_mfma_f32_16x16x32_bf16 v[38:41], v[150:153], v[180:183], v[38:41]
	v_mfma_f32_16x16x32_bf16 v[34:37], v[158:161], v[180:183], v[34:37]
	v_mfma_f32_16x16x32_bf16 v[22:25], v[150:153], v[188:191], v[22:25]
	v_mfma_f32_16x16x32_bf16 v[18:21], v[158:161], v[188:191], v[18:21]
	v_mfma_f32_16x16x32_bf16 v[6:9], v[150:153], v[196:199], v[6:9]
	v_mfma_f32_16x16x32_bf16 v[2:5], v[158:161], v[196:199], v[2:5]
	v_mfma_f32_16x16x32_bf16 v[50:53], v[150:153], v[166:169], v[50:53]
	s_setprio 0
	v_mfma_f32_16x16x32_bf16 v[54:57], v[158:161], v[166:169], v[54:57]
	s_barrier
	s_add_i32 s34, 0, 0x18000
	s_add_i32 s35, 0, 0x1c000
	v_add_u32_e32 v70, s34, v205
	v_add_u32_e32 v158, s35, v205
	ds_read_b128 v[58:61], v70
	ds_read_b128 v[62:65], v70 offset:1024
	ds_read_b128 v[66:69], v70 offset:2048
	ds_read_b128 v[70:73], v70 offset:3072
	ds_read_b128 v[146:149], v158
	ds_read_b128 v[150:153], v158 offset:1024
	ds_read_b128 v[154:157], v158 offset:2048
	ds_read_b128 v[158:161], v158 offset:3072
	s_add_u32 s46, s94, 0x80000
	s_addc_u32 s47, s95, 0
	s_mov_b32 m0, s69
	v_lshl_add_u64 v[212:213], s[46:47], 0, v[0:1]
	ds_read_b128 v[162:165], v207 offset:32768
	ds_read_b128 v[166:169], v207 offset:33792
	ds_read_b128 v[170:173], v207 offset:34816
	ds_read_b128 v[180:183], v207 offset:35840
	ds_read_b128 v[184:187], v207 offset:36864
	ds_read_b128 v[188:191], v207 offset:37888
	ds_read_b128 v[192:195], v207 offset:38912
	ds_read_b128 v[196:199], v207 offset:39936
	global_load_lds_dwordx4 v[212:213], off
	s_mov_b32 m0, s72
	v_lshl_add_u64 v[212:213], s[46:47], 0, v[174:175]
	global_load_lds_dwordx4 v[212:213], off
	s_setprio 1
	s_waitcnt vmcnt(8) lgkmcnt(0)
	s_barrier
	v_mfma_f32_16x16x32_bf16 v[142:145], v[58:61], v[162:165], v[142:145]
	v_mfma_f32_16x16x32_bf16 v[138:141], v[66:69], v[162:165], v[138:141]
	v_mfma_f32_16x16x32_bf16 v[126:129], v[58:61], v[170:173], v[126:129]
	v_mfma_f32_16x16x32_bf16 v[122:125], v[66:69], v[170:173], v[122:125]
	v_mfma_f32_16x16x32_bf16 v[110:113], v[58:61], v[184:187], v[110:113]
	v_mfma_f32_16x16x32_bf16 v[106:109], v[66:69], v[184:187], v[106:109]
	v_mfma_f32_16x16x32_bf16 v[94:97], v[58:61], v[192:195], v[94:97]
	v_mfma_f32_16x16x32_bf16 v[90:93], v[66:69], v[192:195], v[90:93]
	v_mfma_f32_16x16x32_bf16 v[142:145], v[62:65], v[166:169], v[142:145]
	v_mfma_f32_16x16x32_bf16 v[138:141], v[70:73], v[166:169], v[138:141]
	v_mfma_f32_16x16x32_bf16 v[126:129], v[62:65], v[180:183], v[126:129]
	v_mfma_f32_16x16x32_bf16 v[122:125], v[70:73], v[180:183], v[122:125]
	v_mfma_f32_16x16x32_bf16 v[110:113], v[62:65], v[188:191], v[110:113]
	v_mfma_f32_16x16x32_bf16 v[106:109], v[70:73], v[188:191], v[106:109]
	v_mfma_f32_16x16x32_bf16 v[94:97], v[62:65], v[196:199], v[94:97]
	v_mfma_f32_16x16x32_bf16 v[90:93], v[70:73], v[196:199], v[90:93]
	v_mfma_f32_16x16x32_bf16 v[134:137], v[146:149], v[162:165], v[134:137]
	v_mfma_f32_16x16x32_bf16 v[130:133], v[154:157], v[162:165], v[130:133]
	v_mfma_f32_16x16x32_bf16 v[118:121], v[146:149], v[170:173], v[118:121]
	v_mfma_f32_16x16x32_bf16 v[114:117], v[154:157], v[170:173], v[114:117]
	v_mfma_f32_16x16x32_bf16 v[102:105], v[146:149], v[184:187], v[102:105]
	v_mfma_f32_16x16x32_bf16 v[98:101], v[154:157], v[184:187], v[98:101]
	v_mfma_f32_16x16x32_bf16 v[86:89], v[146:149], v[192:195], v[86:89]
	v_mfma_f32_16x16x32_bf16 v[82:85], v[154:157], v[192:195], v[82:85]
	v_mfma_f32_16x16x32_bf16 v[134:137], v[150:153], v[166:169], v[134:137]
	v_mfma_f32_16x16x32_bf16 v[130:133], v[158:161], v[166:169], v[130:133]
	v_mfma_f32_16x16x32_bf16 v[118:121], v[150:153], v[180:183], v[118:121]
	v_mfma_f32_16x16x32_bf16 v[114:117], v[158:161], v[180:183], v[114:117]
	v_mfma_f32_16x16x32_bf16 v[102:105], v[150:153], v[188:191], v[102:105]
	v_mfma_f32_16x16x32_bf16 v[98:101], v[158:161], v[188:191], v[98:101]
	v_mfma_f32_16x16x32_bf16 v[86:89], v[150:153], v[196:199], v[86:89]
	s_setprio 0
	v_mfma_f32_16x16x32_bf16 v[82:85], v[158:161], v[196:199], v[82:85]
	s_barrier
; #define PG8_STAGE(bufoff, gbase, voff) do { _Pragma("unroll") for (int _i = 0; _i < 2; ++_i) \
;         __builtin_amdgcn_global_load_lds((const unsigned*)((const char*)(gbase) + (voff)[_i]), (LAS unsigned*)(lds + (bufoff) + ldsw + _i * 8192), 16, 0, 0); } while (0)
; #define PG8_LDA(dst, b, h) do { _Pragma("unroll") for (int m = 0; m < 4; ++m) _Pragma("unroll") for (int k = 0; k < 2; ++k) dst[m][k] = *(const LAS bf16x8*)(lds + PG8_SA(b, h) + aoff + m * 2048 + k * 1024); } while (0)
; #define PG8_MMA(ai, bj, At, Bt) do { __builtin_amdgcn_s_setprio(1); _Pragma("unroll") for (int m = 0; m < 4; ++m) _Pragma("unroll") for (int n = 0; n < 2; ++n) _Pragma("unroll") for (int k = 0; k < 2; ++k) \
;         acc[ai][bj][m][n] = __builtin_amdgcn_mfma_f32_16x16x32_bf16(Bt[n][k], At[m][k], acc[ai][bj][m][n], 0, 0, 0); __builtin_amdgcn_s_setprio(0); } while (0)
; #define PG8_WAIT_V(n) asm volatile("s_waitcnt vmcnt(" #n ")" ::: "memory")
; #define PG8_WAIT_L(n) asm volatile("s_waitcnt lgkmcnt(" #n ")" ::: "memory")
; #define PG8_BAR __builtin_amdgcn_s_barrier()
; #define PG8_SCHED __builtin_amdgcn_sched_barrier(0)
; template <class Epi, int AMODE>
; __device__ __forceinline__ void gemm_phase(LAS unsigned char* lds, const Gemm g, const StaticOrder& S, const Epi& E, int stagger_us, int tid_in) {
;     ...
;             PG8_LDA(At, 1, 1); PG8_STAGE(PG8_SB(1, 0), b3, voffB); PG8_STAGE(PG8_SB(1, 1), b3 + hstepB, voffB); PG8_STAGE(PG8_SA(1, 0), a3, voffA);
;             PG8_WAIT_V(8); PG8_WAIT_L(0); PG8_BAR; PG8_MMA(1, 0, At, B0); PG8_MMA(1, 1, At, B1); PG8_BAR; PG8_SCHED;
;         }
;         if (wr == 0) PG8_BAR;
	s_add_i32 s34, s34, s13
	v_lshl_add_u64 v[200:201], v[200:201], 0, s[74:75]
	s_mov_b32 m0, s34
	ds_read_b128 v[162:165], v207 offset:49152
	ds_read_b128 v[166:169], v207 offset:50176
	ds_read_b128 v[170:173], v207 offset:51200
	ds_read_b128 v[180:183], v207 offset:52224
	ds_read_b128 v[184:187], v207 offset:53248
	ds_read_b128 v[188:191], v207 offset:54272
	ds_read_b128 v[192:195], v207 offset:55296
	ds_read_b128 v[196:199], v207 offset:56320
	global_load_lds_dwordx4 v[200:201], off
	s_add_i32 m0, s34, 0x2000
	s_add_u32 s6, s6, 0x80080
	v_lshl_add_u64 v[200:201], v[202:203], 0, s[74:75]
	s_addc_u32 s7, s7, 0
	s_add_i32 s34, s35, s13
	global_load_lds_dwordx4 v[200:201], off
	s_mov_b32 m0, s34
	v_lshl_add_u64 v[200:201], s[6:7], 0, v[0:1]
	global_load_lds_dwordx4 v[200:201], off
	s_add_i32 m0, s34, 0x2000
	v_lshl_add_u64 v[200:201], s[6:7], 0, v[174:175]
	global_load_lds_dwordx4 v[200:201], off
	s_mov_b32 m0, s91
	v_lshl_add_u64 v[200:201], v[208:209], 0, s[74:75]
	global_load_lds_dwordx4 v[200:201], off
	s_mov_b32 m0, s96
	v_lshl_add_u64 v[200:201], v[210:211], 0, s[74:75]
	global_load_lds_dwordx4 v[200:201], off
	s_setprio 1
	s_waitcnt vmcnt(8) lgkmcnt(0)
	s_barrier
	v_mfma_f32_16x16x32_bf16 v[78:81], v[58:61], v[162:165], v[78:81]
	v_mfma_f32_16x16x32_bf16 v[74:77], v[66:69], v[162:165], v[74:77]
	v_mfma_f32_16x16x32_bf16 v[46:49], v[58:61], v[170:173], v[46:49]
	v_mfma_f32_16x16x32_bf16 v[42:45], v[66:69], v[170:173], v[42:45]
	v_mfma_f32_16x16x32_bf16 v[30:33], v[58:61], v[184:187], v[30:33]
	v_mfma_f32_16x16x32_bf16 v[26:29], v[66:69], v[184:187], v[26:29]
	v_mfma_f32_16x16x32_bf16 v[14:17], v[58:61], v[192:195], v[14:17]
	v_mfma_f32_16x16x32_bf16 v[10:13], v[66:69], v[192:195], v[10:13]
	v_mfma_f32_16x16x32_bf16 v[78:81], v[62:65], v[166:169], v[78:81]
	v_mfma_f32_16x16x32_bf16 v[74:77], v[70:73], v[166:169], v[74:77]
	v_mfma_f32_16x16x32_bf16 v[46:49], v[62:65], v[180:183], v[46:49]
	v_mfma_f32_16x16x32_bf16 v[42:45], v[70:73], v[180:183], v[42:45]
	v_mfma_f32_16x16x32_bf16 v[30:33], v[62:65], v[188:191], v[30:33]
	v_mfma_f32_16x16x32_bf16 v[26:29], v[70:73], v[188:191], v[26:29]
	v_mfma_f32_16x16x32_bf16 v[14:17], v[62:65], v[196:199], v[14:17]
	v_mfma_f32_16x16x32_bf16 v[10:13], v[70:73], v[196:199], v[10:13]
	v_mfma_f32_16x16x32_bf16 v[50:53], v[146:149], v[162:165], v[50:53]
	v_mfma_f32_16x16x32_bf16 v[70:73], v[150:153], v[166:169], v[50:53]
	v_mfma_f32_16x16x32_bf16 v[50:53], v[154:157], v[162:165], v[54:57]
	v_mfma_f32_16x16x32_bf16 v[38:41], v[146:149], v[170:173], v[38:41]
	v_mfma_f32_16x16x32_bf16 v[34:37], v[154:157], v[170:173], v[34:37]
	v_mfma_f32_16x16x32_bf16 v[22:25], v[146:149], v[184:187], v[22:25]
	v_mfma_f32_16x16x32_bf16 v[18:21], v[154:157], v[184:187], v[18:21]
	v_mfma_f32_16x16x32_bf16 v[6:9], v[146:149], v[192:195], v[6:9]
	v_mfma_f32_16x16x32_bf16 v[2:5], v[154:157], v[192:195], v[2:5]
	v_mfma_f32_16x16x32_bf16 v[66:69], v[158:161], v[166:169], v[50:53]
	v_mfma_f32_16x16x32_bf16 v[38:41], v[150:153], v[180:183], v[38:41]
	v_mfma_f32_16x16x32_bf16 v[34:37], v[158:161], v[180:183], v[34:37]
	v_mfma_f32_16x16x32_bf16 v[22:25], v[150:153], v[188:191], v[22:25]
	v_mfma_f32_16x16x32_bf16 v[18:21], v[158:161], v[188:191], v[18:21]
	v_mfma_f32_16x16x32_bf16 v[6:9], v[150:153], v[196:199], v[6:9]
	s_setprio 0
	v_mfma_f32_16x16x32_bf16 v[2:5], v[158:161], v[196:199], v[2:5]
	s_barrier
	s_add_i32 s31, s31, 2
	s_add_u32 s29, s29, 0x100
	s_addc_u32 s30, s30, 0
	s_cmp_gt_u32 s31, 29
	s_mov_b64 s[46:47], s[4:5]
	s_cbranch_scc0 .LBB0_1199
	s_and_b64 vcc, exec, s[56:57]
	s_cbranch_vccz .LBB0_1202
	s_barrier

; #define PG8_STAGE(bufoff, gbase, voff) do { _Pragma("unroll") for (int _i = 0; _i < 2; ++_i) \
;         __builtin_amdgcn_global_load_lds((const unsigned*)((const char*)(gbase) + (voff)[_i]), (LAS unsigned*)(lds + (bufoff) + ldsw + _i * 8192), 16, 0, 0); } while (0)
; #define PG8_LDA(dst, b, h) do { _Pragma("unroll") for (int m = 0; m < 4; ++m) _Pragma("unroll") for (int k = 0; k < 2; ++k) dst[m][k] = *(const LAS bf16x8*)(lds + PG8_SA(b, h) + aoff + m * 2048 + k * 1024); } while (0)
; #define PG8_LDB(dst, b, h) do { _Pragma("unroll") for (int n = 0; n < 2; ++n) _Pragma("unroll") for (int k = 0; k < 2; ++k) dst[n][k] = *(const LAS bf16x8*)(lds + PG8_SB(b, h) + boff + n * 2048 + k * 1024); } while (0)
; #define PG8_WAIT_V(n) asm volatile("s_waitcnt vmcnt(" #n ")" ::: "memory")
; #define PG8_WAIT_L(n) asm volatile("s_waitcnt lgkmcnt(" #n ")" ::: "memory")
; #define PG8_BAR __builtin_amdgcn_s_barrier()
; #define PG8_SCHED __builtin_amdgcn_sched_barrier(0)
; template <class Epi, int AMODE>
; __device__ __forceinline__ void gemm_phase(LAS unsigned char* lds, const Gemm g, const StaticOrder& S, const Epi& E, int stagger_us, int tid_in) {
;     ...
;             PG8_LDB(B0, 0, 0); PG8_LDB(B1, 0, 1); PG8_SCHED; PG8_LDA(At, 0, 0); PG8_STAGE(PG8_SA(1, 1), a1 + hstepA, voffA);
;             PG8_WAIT_V(8); PG8_WAIT_L(0); PG8_BAR; PG8_MMA(0, 0, At, B0); PG8_MMA(0, 1, At, B1); PG8_BAR; PG8_SCHED;
;     __device__ __forceinline__ void operator()(f32x4 (&acc)[2][2][4][2], const Unit& u, int wr, int wc, int fr, int fq) const {
;     ...
;         const int tok0 = 252 * u.pm + 126 * wr - 1;
;         {
;             const int tq = tok0 + 8 * fr; const int tA = tq < 0 ? 0 : (tq > TOK - 1 ? TOK - 1 : tq), tB = (tq + 7) > TOK - 1 ? TOK - 1 : (tq + 7);
;             const int bA = batch_of(tA), bB = batch_of(tB); const bool same = __all(bA == bB);
;             const float* bp0 = bias + 256 * u.pn + 32 * wc + 8 * fq;
;             f32x4 bvA[2][2]; float sq[8];
; #pragma unroll
;             for (int am = 0; am < 8; ++am) { int tok = tq + am; tok = tok < 0 ? 0 : (tok > TOK - 1 ? TOK - 1 : tok); sq[am] = LDG(float, ssq + tok); }
; #pragma unroll
;             for (int bj = 0; bj < 2; ++bj)
; #pragma unroll
;                 for (int n = 0; n < 2; ++n) bvA[bj][n] = LDG(f32x4, bp0 + (size_t)bA * (2 * DFF) + bj * HALF + 4 * n);
.LBB0_1298:
	s_ashr_i32 s47, s46, 31
	s_lshl_b64 s[6:7], s[46:47], 20
	s_add_u32 s96, s9, s6
	s_addc_u32 s97, s72, s7
	s_and_b64 s[6:7], s[42:43], exec
	s_cselect_b32 s27, s97, s5
	s_cselect_b32 s28, s96, s4
	s_add_u32 s29, s4, 0x100
	v_mov_b32_e32 v2, 0
	s_addc_u32 s30, s5, 0
	s_mov_b32 s31, -2
	s_mul_i32 s6, s26, 0xfc
	v_add_u32_e32 v222, s6, v197
	v_med3_i32 v240, v222, 0, v238
	v_add_u32_e32 v241, 0xffffe000, v240
	v_lshrrev_b32_e32 v241, 12, v241
	v_add_u32_e32 v241, 4, v241
	v_lshrrev_b32_e32 v242, 11, v240
	v_mov_b32_e32 v243, 0x2000
	v_cmp_gt_i32_e64 s[6:7], v243, v222
	s_nop 1
	v_cndmask_b32_e64 v241, v241, v242, s[6:7]
	s_lshl_b32 s6, s92, 8
	s_ashr_i32 s7, s6, 31
	v_lshl_add_u64 v[236:237], s[6:7], 2, v[184:185]
	v_mad_u64_u32 v[236:237], s[6:7], v241, s15, v[236:237]
	v_med3_i32 v224, v222, 0, v238
	v_lshlrev_b32_e32 v224, 2, v224
	global_load_dword v224, v224, s[56:57]
	v_add_u32_e32 v228, 1, v222
	v_med3_i32 v228, v228, 0, v238
	v_lshlrev_b32_e32 v228, 2, v228
	global_load_dword v228, v228, s[56:57]
	v_add_u32_e32 v231, 2, v222
	v_med3_i32 v231, v231, 0, v238
	v_lshlrev_b32_e32 v231, 2, v231
	global_load_dword v231, v231, s[56:57]
	v_add_u32_e32 v233, 3, v222
	v_med3_i32 v233, v233, 0, v238
	v_lshlrev_b32_e32 v233, 2, v233
	global_load_dword v233, v233, s[56:57]
	v_add_u32_e32 v234, 4, v222
	v_med3_i32 v234, v234, 0, v238
	v_lshlrev_b32_e32 v234, 2, v234
	global_load_dword v234, v234, s[56:57]
	v_add_u32_e32 v239, 5, v222
	v_med3_i32 v239, v239, 0, v238
	v_lshlrev_b32_e32 v239, 2, v239
	global_load_dword v239, v239, s[56:57]
	v_add_u32_e32 v252, 6, v222
	v_med3_i32 v252, v252, 0, v238
	v_lshlrev_b32_e32 v252, 2, v252
	global_load_dword v252, v252, s[56:57]
	v_add_u32_e32 v253, 7, v222
	v_med3_i32 v253, v253, 0, v238
	v_lshlrev_b32_e32 v253, 2, v253
	global_load_dword v253, v253, s[56:57]
	global_load_dwordx4 v[240:243], v[236:237], off
	global_load_dwordx4 v[244:247], v[236:237], off offset:16
	global_load_dwordx4 v[248:251], v[236:237], off offset:512
	global_load_dwordx2 v[222:223], v[236:237], off offset:528
	s_nop 0
	global_load_dwordx2 v[236:237], v[236:237], off offset:536
	v_mov_b32_e32 v3, v2
	v_mov_b32_e32 v4, v2
	v_mov_b32_e32 v5, v2
	v_mov_b32_e32 v14, v2
	v_mov_b32_e32 v15, v2
	v_mov_b32_e32 v16, v2
	v_mov_b32_e32 v17, v2
	v_mov_b32_e32 v10, v2
	v_mov_b32_e32 v11, v2
	v_mov_b32_e32 v12, v2
	v_mov_b32_e32 v13, v2
	v_mov_b32_e32 v26, v2
	v_mov_b32_e32 v27, v2
	v_mov_b32_e32 v28, v2
	v_mov_b32_e32 v29, v2
	v_mov_b32_e32 v6, v2
	v_mov_b32_e32 v7, v2
	v_mov_b32_e32 v8, v2
	v_mov_b32_e32 v9, v2
	v_mov_b32_e32 v42, v2
	v_mov_b32_e32 v43, v2
	v_mov_b32_e32 v44, v2
	v_mov_b32_e32 v45, v2
	v_mov_b32_e32 v30, v2
	v_mov_b32_e32 v31, v2
	v_mov_b32_e32 v32, v2
	v_mov_b32_e32 v33, v2
	v_mov_b32_e32 v58, v2
	v_mov_b32_e32 v59, v2
	v_mov_b32_e32 v60, v2
	v_mov_b32_e32 v61, v2
	v_mov_b32_e32 v74, v2
	v_mov_b32_e32 v75, v2
	v_mov_b32_e32 v76, v2
	v_mov_b32_e32 v77, v2
	v_mov_b32_e32 v22, v2
	v_mov_b32_e32 v23, v2
	v_mov_b32_e32 v24, v2
	v_mov_b32_e32 v25, v2
	v_mov_b32_e32 v34, v2
	v_mov_b32_e32 v35, v2
	v_mov_b32_e32 v36, v2
	v_mov_b32_e32 v37, v2
	v_mov_b32_e32 v18, v2
	v_mov_b32_e32 v19, v2
	v_mov_b32_e32 v20, v2
	v_mov_b32_e32 v21, v2
	v_mov_b32_e32 v50, v2
	v_mov_b32_e32 v51, v2
	v_mov_b32_e32 v52, v2
	v_mov_b32_e32 v53, v2
	v_mov_b32_e32 v38, v2
	v_mov_b32_e32 v39, v2
	v_mov_b32_e32 v40, v2
	v_mov_b32_e32 v41, v2
	v_mov_b32_e32 v46, v2
	v_mov_b32_e32 v47, v2
	v_mov_b32_e32 v48, v2
	v_mov_b32_e32 v49, v2
	v_mov_b32_e32 v54, v2
	v_mov_b32_e32 v55, v2
	v_mov_b32_e32 v56, v2
	v_mov_b32_e32 v57, v2
	v_mov_b32_e32 v66, v2
	v_mov_b32_e32 v67, v2
	v_mov_b32_e32 v68, v2
	v_mov_b32_e32 v69, v2
	v_mov_b32_e32 v78, v2
	v_mov_b32_e32 v79, v2
	v_mov_b32_e32 v80, v2
	v_mov_b32_e32 v81, v2
	v_mov_b32_e32 v62, v2
	v_mov_b32_e32 v63, v2
	v_mov_b32_e32 v64, v2
	v_mov_b32_e32 v65, v2
	v_mov_b32_e32 v70, v2
	v_mov_b32_e32 v71, v2
	v_mov_b32_e32 v72, v2
	v_mov_b32_e32 v73, v2
	v_mov_b32_e32 v86, v2
	v_mov_b32_e32 v87, v2
	v_mov_b32_e32 v88, v2
	v_mov_b32_e32 v89, v2
	v_mov_b32_e32 v94, v2
	v_mov_b32_e32 v95, v2
	v_mov_b32_e32 v96, v2
	v_mov_b32_e32 v97, v2
	v_mov_b32_e32 v98, v2
	v_mov_b32_e32 v99, v2
	v_mov_b32_e32 v100, v2
	v_mov_b32_e32 v101, v2
	v_mov_b32_e32 v106, v2
	v_mov_b32_e32 v107, v2
	v_mov_b32_e32 v108, v2
	v_mov_b32_e32 v109, v2
	v_mov_b32_e32 v82, v2
	v_mov_b32_e32 v83, v2
	v_mov_b32_e32 v84, v2
	v_mov_b32_e32 v85, v2
	v_mov_b32_e32 v90, v2
	v_mov_b32_e32 v91, v2
	v_mov_b32_e32 v92, v2
	v_mov_b32_e32 v93, v2
	v_mov_b32_e32 v102, v2
	v_mov_b32_e32 v103, v2
	v_mov_b32_e32 v104, v2
	v_mov_b32_e32 v105, v2
	v_mov_b32_e32 v110, v2
	v_mov_b32_e32 v111, v2
	v_mov_b32_e32 v112, v2
	v_mov_b32_e32 v113, v2
	v_mov_b32_e32 v114, v2
	v_mov_b32_e32 v115, v2
	v_mov_b32_e32 v116, v2
	v_mov_b32_e32 v117, v2
	v_mov_b32_e32 v118, v2
	v_mov_b32_e32 v119, v2
	v_mov_b32_e32 v120, v2
	v_mov_b32_e32 v121, v2
	v_mov_b32_e32 v122, v2
	v_mov_b32_e32 v123, v2
	v_mov_b32_e32 v124, v2
	v_mov_b32_e32 v125, v2
	v_mov_b32_e32 v126, v2
	v_mov_b32_e32 v127, v2
	v_mov_b32_e32 v128, v2
	v_mov_b32_e32 v129, v2
	s_add_u32 s4, s44, 0x100
	s_addc_u32 s5, s45, 0
	s_add_i32 s34, 0, 0x10000
	s_cmp_eq_u32 s31, 28
	s_cselect_b32 s43, s95, s5
	s_cselect_b32 s42, s94, s4
	s_cselect_b32 s7, s27, s30
	s_cselect_b32 s6, s28, s29
	s_add_i32 s35, 0, 0x14000
	v_add_u32_e32 v142, s34, v196
	v_add_u32_e32 v158, s35, v196
	ds_read_b128 v[130:133], v142
	ds_read_b128 v[134:137], v142 offset:1024
	ds_read_b128 v[138:141], v142 offset:2048
	ds_read_b128 v[142:145], v142 offset:3072
	ds_read_b128 v[146:149], v158
	ds_read_b128 v[150:153], v158 offset:1024
	ds_read_b128 v[154:157], v158 offset:2048
	ds_read_b128 v[158:161], v158 offset:3072
	v_lshl_add_u64 v[194:195], s[44:45], 0, v[186:187]
	s_add_i32 m0, s93, 0xc000
	ds_read_b128 v[162:165], v201
	ds_read_b128 v[166:169], v201 offset:1024
	ds_read_b128 v[170:173], v201 offset:2048
	ds_read_b128 v[174:177], v201 offset:3072
	ds_read_b128 v[190:193], v201 offset:4096
	ds_read_b128 v[202:205], v201 offset:5120
	ds_read_b128 v[206:209], v201 offset:6144
	ds_read_b128 v[210:213], v201 offset:7168
	global_load_lds_dwordx4 v[194:195], off
	s_add_i32 m0, s93, 0xe000
	v_lshl_add_u64 v[194:195], s[44:45], 0, v[188:189]
	global_load_lds_dwordx4 v[194:195], off
	s_setprio 1
	s_waitcnt lgkmcnt(0)
	s_barrier
; #define PG8_STAGE(bufoff, gbase, voff) do { _Pragma("unroll") for (int _i = 0; _i < 2; ++_i) \
;         __builtin_amdgcn_global_load_lds((const unsigned*)((const char*)(gbase) + (voff)[_i]), (LAS unsigned*)(lds + (bufoff) + ldsw + _i * 8192), 16, 0, 0); } while (0)
; #define PG8_LDA(dst, b, h) do { _Pragma("unroll") for (int m = 0; m < 4; ++m) _Pragma("unroll") for (int k = 0; k < 2; ++k) dst[m][k] = *(const LAS bf16x8*)(lds + PG8_SA(b, h) + aoff + m * 2048 + k * 1024); } while (0)
; #define PG8_MMA(ai, bj, At, Bt) do { __builtin_amdgcn_s_setprio(1); _Pragma("unroll") for (int m = 0; m < 4; ++m) _Pragma("unroll") for (int n = 0; n < 2; ++n) _Pragma("unroll") for (int k = 0; k < 2; ++k) \
;         acc[ai][bj][m][n] = __builtin_amdgcn_mfma_f32_16x16x32_bf16(Bt[n][k], At[m][k], acc[ai][bj][m][n], 0, 0, 0); __builtin_amdgcn_s_setprio(0); } while (0)
; #define PG8_WAIT_V(n) asm volatile("s_waitcnt vmcnt(" #n ")" ::: "memory")
; #define PG8_WAIT_L(n) asm volatile("s_waitcnt lgkmcnt(" #n ")" ::: "memory")
; #define PG8_BAR __builtin_amdgcn_s_barrier()
; #define PG8_SCHED __builtin_amdgcn_sched_barrier(0)
; template <class Epi, int AMODE>
; __device__ __forceinline__ void gemm_phase(LAS unsigned char* lds, const Gemm g, const StaticOrder& S, const Epi& E, int stagger_us, int tid_in) {
;     ...
;             PG8_WAIT_V(8); PG8_WAIT_L(0); PG8_BAR; PG8_MMA(0, 0, At, B0); PG8_MMA(0, 1, At, B1); PG8_BAR; PG8_SCHED;
;             PG8_LDA(At, 0, 1); PG8_STAGE(PG8_SB(0, 0), b2, voffB); PG8_STAGE(PG8_SB(0, 1), b2 + hstepB, voffB); PG8_STAGE(PG8_SA(0, 0), a2, voffA);
;             PG8_WAIT_V(8); PG8_WAIT_L(0); PG8_BAR; PG8_MMA(1, 0, At, B0); PG8_MMA(1, 1, At, B1); PG8_BAR; PG8_SCHED;
	v_mfma_f32_16x16x32_bf16 v[126:129], v[130:133], v[162:165], v[126:129]
	v_mfma_f32_16x16x32_bf16 v[122:125], v[138:141], v[162:165], v[122:125]
	v_mfma_f32_16x16x32_bf16 v[118:121], v[130:133], v[170:173], v[118:121]
	v_mfma_f32_16x16x32_bf16 v[114:117], v[138:141], v[170:173], v[114:117]
	v_mfma_f32_16x16x32_bf16 v[110:113], v[130:133], v[190:193], v[110:113]
	v_mfma_f32_16x16x32_bf16 v[102:105], v[138:141], v[190:193], v[102:105]
	v_mfma_f32_16x16x32_bf16 v[90:93], v[130:133], v[206:209], v[90:93]
	v_mfma_f32_16x16x32_bf16 v[82:85], v[138:141], v[206:209], v[82:85]
	v_mfma_f32_16x16x32_bf16 v[126:129], v[134:137], v[166:169], v[126:129]
	v_mfma_f32_16x16x32_bf16 v[122:125], v[142:145], v[166:169], v[122:125]
	v_mfma_f32_16x16x32_bf16 v[118:121], v[134:137], v[174:177], v[118:121]
	v_mfma_f32_16x16x32_bf16 v[114:117], v[142:145], v[174:177], v[114:117]
	v_mfma_f32_16x16x32_bf16 v[110:113], v[134:137], v[202:205], v[110:113]
	v_mfma_f32_16x16x32_bf16 v[102:105], v[142:145], v[202:205], v[102:105]
	v_mfma_f32_16x16x32_bf16 v[90:93], v[134:137], v[210:213], v[90:93]
	v_mfma_f32_16x16x32_bf16 v[82:85], v[142:145], v[210:213], v[82:85]
	v_mfma_f32_16x16x32_bf16 v[106:109], v[146:149], v[162:165], v[106:109]
	v_mfma_f32_16x16x32_bf16 v[98:101], v[154:157], v[162:165], v[98:101]
	v_mfma_f32_16x16x32_bf16 v[94:97], v[146:149], v[170:173], v[94:97]
	v_mfma_f32_16x16x32_bf16 v[86:89], v[154:157], v[170:173], v[86:89]
	v_mfma_f32_16x16x32_bf16 v[70:73], v[146:149], v[190:193], v[70:73]
	v_mfma_f32_16x16x32_bf16 v[62:65], v[154:157], v[190:193], v[62:65]
	v_mfma_f32_16x16x32_bf16 v[78:81], v[146:149], v[206:209], v[78:81]
	v_mfma_f32_16x16x32_bf16 v[66:69], v[154:157], v[206:209], v[66:69]
	v_mfma_f32_16x16x32_bf16 v[106:109], v[150:153], v[166:169], v[106:109]
	v_mfma_f32_16x16x32_bf16 v[98:101], v[158:161], v[166:169], v[98:101]
	v_mfma_f32_16x16x32_bf16 v[94:97], v[150:153], v[174:177], v[94:97]
	v_mfma_f32_16x16x32_bf16 v[86:89], v[158:161], v[174:177], v[86:89]
	v_mfma_f32_16x16x32_bf16 v[70:73], v[150:153], v[202:205], v[70:73]
	v_mfma_f32_16x16x32_bf16 v[62:65], v[158:161], v[202:205], v[62:65]
	v_mfma_f32_16x16x32_bf16 v[78:81], v[150:153], v[210:213], v[78:81]
	s_setprio 0
	v_mfma_f32_16x16x32_bf16 v[66:69], v[158:161], v[210:213], v[66:69]
	s_barrier
	s_add_i32 s34, s34, s91
	v_lshl_add_u64 v[194:195], s[6:7], 0, v[0:1]
	s_mov_b32 m0, s34
	ds_read_b128 v[162:165], v201 offset:16384
	ds_read_b128 v[166:169], v201 offset:17408
	ds_read_b128 v[170:173], v201 offset:18432
	ds_read_b128 v[174:177], v201 offset:19456
	ds_read_b128 v[190:193], v201 offset:20480
	ds_read_b128 v[202:205], v201 offset:21504
	ds_read_b128 v[206:209], v201 offset:22528
	ds_read_b128 v[210:213], v201 offset:23552
	global_load_lds_dwordx4 v[194:195], off
	s_add_i32 m0, s34, 0x2000
	s_add_u32 s44, s6, 0x80000
	v_lshl_add_u64 v[214:215], s[6:7], 0, v[182:183]
	s_addc_u32 s45, s7, 0
	s_add_i32 s34, s35, s91
	global_load_lds_dwordx4 v[214:215], off
	v_lshl_add_u64 v[216:217], s[44:45], 0, v[0:1]
	s_mov_b32 m0, s34
	v_lshl_add_u64 v[218:219], s[42:43], 0, v[180:181]
	global_load_lds_dwordx4 v[216:217], off
	s_add_i32 m0, s34, 0x2000
	v_lshl_add_u64 v[216:217], s[44:45], 0, v[182:183]
	global_load_lds_dwordx4 v[216:217], off
	s_mov_b32 m0, s93
	v_lshl_add_u64 v[216:217], s[42:43], 0, v[178:179]
	global_load_lds_dwordx4 v[216:217], off
	s_mov_b32 m0, s83
	s_nop 0
	global_load_lds_dwordx4 v[218:219], off
	s_setprio 1
	s_waitcnt lgkmcnt(0)
	s_barrier
	v_mfma_f32_16x16x32_bf16 v[54:57], v[130:133], v[162:165], v[54:57]
	v_mfma_f32_16x16x32_bf16 v[46:49], v[138:141], v[162:165], v[46:49]
	v_mfma_f32_16x16x32_bf16 v[38:41], v[130:133], v[170:173], v[38:41]
	v_mfma_f32_16x16x32_bf16 v[50:53], v[138:141], v[170:173], v[50:53]
	v_mfma_f32_16x16x32_bf16 v[18:21], v[130:133], v[190:193], v[18:21]
	v_mfma_f32_16x16x32_bf16 v[34:37], v[138:141], v[190:193], v[34:37]
	v_mfma_f32_16x16x32_bf16 v[22:25], v[130:133], v[206:209], v[22:25]
	v_mfma_f32_16x16x32_bf16 v[74:77], v[138:141], v[206:209], v[74:77]
	v_mfma_f32_16x16x32_bf16 v[54:57], v[134:137], v[166:169], v[54:57]
	v_mfma_f32_16x16x32_bf16 v[46:49], v[142:145], v[166:169], v[46:49]
	v_mfma_f32_16x16x32_bf16 v[38:41], v[134:137], v[174:177], v[38:41]
	v_mfma_f32_16x16x32_bf16 v[50:53], v[142:145], v[174:177], v[50:53]
	v_mfma_f32_16x16x32_bf16 v[18:21], v[134:137], v[202:205], v[18:21]
	v_mfma_f32_16x16x32_bf16 v[34:37], v[142:145], v[202:205], v[34:37]
	v_mfma_f32_16x16x32_bf16 v[22:25], v[134:137], v[210:213], v[22:25]
	v_mfma_f32_16x16x32_bf16 v[74:77], v[142:145], v[210:213], v[74:77]
	v_mfma_f32_16x16x32_bf16 v[58:61], v[146:149], v[162:165], v[58:61]
	v_mfma_f32_16x16x32_bf16 v[30:33], v[154:157], v[162:165], v[30:33]
	v_mfma_f32_16x16x32_bf16 v[42:45], v[146:149], v[170:173], v[42:45]
	v_mfma_f32_16x16x32_bf16 v[6:9], v[154:157], v[170:173], v[6:9]
	v_mfma_f32_16x16x32_bf16 v[26:29], v[146:149], v[190:193], v[26:29]
	v_mfma_f32_16x16x32_bf16 v[10:13], v[154:157], v[190:193], v[10:13]
	v_mfma_f32_16x16x32_bf16 v[14:17], v[146:149], v[206:209], v[14:17]
	v_mfma_f32_16x16x32_bf16 v[2:5], v[154:157], v[206:209], v[2:5]
	v_mfma_f32_16x16x32_bf16 v[58:61], v[150:153], v[166:169], v[58:61]
	v_mfma_f32_16x16x32_bf16 v[30:33], v[158:161], v[166:169], v[30:33]
	v_mfma_f32_16x16x32_bf16 v[42:45], v[150:153], v[174:177], v[42:45]
	v_mfma_f32_16x16x32_bf16 v[6:9], v[158:161], v[174:177], v[6:9]
	v_mfma_f32_16x16x32_bf16 v[26:29], v[150:153], v[202:205], v[26:29]
	v_mfma_f32_16x16x32_bf16 v[10:13], v[158:161], v[202:205], v[10:13]
	v_mfma_f32_16x16x32_bf16 v[14:17], v[150:153], v[210:213], v[14:17]
	s_setprio 0
	v_mfma_f32_16x16x32_bf16 v[2:5], v[158:161], v[210:213], v[2:5]
	s_barrier
; #define PG8_STAGE(bufoff, gbase, voff) do { _Pragma("unroll") for (int _i = 0; _i < 2; ++_i) \
;         __builtin_amdgcn_global_load_lds((const unsigned*)((const char*)(gbase) + (voff)[_i]), (LAS unsigned*)(lds + (bufoff) + ldsw + _i * 8192), 16, 0, 0); } while (0)
; #define PG8_LDA(dst, b, h) do { _Pragma("unroll") for (int m = 0; m < 4; ++m) _Pragma("unroll") for (int k = 0; k < 2; ++k) dst[m][k] = *(const LAS bf16x8*)(lds + PG8_SA(b, h) + aoff + m * 2048 + k * 1024); } while (0)
; #define PG8_LDB(dst, b, h) do { _Pragma("unroll") for (int n = 0; n < 2; ++n) _Pragma("unroll") for (int k = 0; k < 2; ++k) dst[n][k] = *(const LAS bf16x8*)(lds + PG8_SB(b, h) + boff + n * 2048 + k * 1024); } while (0)
; #define PG8_MMA(ai, bj, At, Bt) do { __builtin_amdgcn_s_setprio(1); _Pragma("unroll") for (int m = 0; m < 4; ++m) _Pragma("unroll") for (int n = 0; n < 2; ++n) _Pragma("unroll") for (int k = 0; k < 2; ++k) \
;         acc[ai][bj][m][n] = __builtin_amdgcn_mfma_f32_16x16x32_bf16(Bt[n][k], At[m][k], acc[ai][bj][m][n], 0, 0, 0); __builtin_amdgcn_s_setprio(0); } while (0)
; #define PG8_WAIT_V(n) asm volatile("s_waitcnt vmcnt(" #n ")" ::: "memory")
; #define PG8_WAIT_L(n) asm volatile("s_waitcnt lgkmcnt(" #n ")" ::: "memory")
; #define PG8_BAR __builtin_amdgcn_s_barrier()
; #define PG8_SCHED __builtin_amdgcn_sched_barrier(0)
; template <class Epi, int AMODE>
; __device__ __forceinline__ void gemm_phase(LAS unsigned char* lds, const Gemm g, const StaticOrder& S, const Epi& E, int stagger_us, int tid_in) {
;     ...
;             PG8_LDB(B0, 1, 0); PG8_LDB(B1, 1, 1); PG8_SCHED; PG8_LDA(At, 1, 0); PG8_STAGE(PG8_SA(0, 1), a2 + hstepA, voffA);
;             PG8_WAIT_V(8); PG8_WAIT_L(0); PG8_BAR; PG8_MMA(0, 0, At, B0); PG8_MMA(0, 1, At, B1); PG8_BAR; PG8_SCHED;
;             PG8_LDA(At, 1, 1); PG8_STAGE(PG8_SB(1, 0), b3, voffB); PG8_STAGE(PG8_SB(1, 1), b3 + hstepB, voffB); PG8_STAGE(PG8_SA(1, 0), a3, voffA);
;             PG8_WAIT_V(8); PG8_WAIT_L(0); PG8_BAR; PG8_MMA(1, 0, At, B0); PG8_MMA(1, 1, At, B1); PG8_BAR; PG8_SCHED;
	s_add_i32 s34, 0, 0x18000
	s_add_i32 s35, 0, 0x1c000
	v_add_u32_e32 v142, s34, v196
	v_add_u32_e32 v158, s35, v196
	ds_read_b128 v[130:133], v142
	ds_read_b128 v[134:137], v142 offset:1024
	ds_read_b128 v[138:141], v142 offset:2048
	ds_read_b128 v[142:145], v142 offset:3072
	ds_read_b128 v[146:149], v158
	ds_read_b128 v[150:153], v158 offset:1024
	ds_read_b128 v[154:157], v158 offset:2048
	ds_read_b128 v[158:161], v158 offset:3072
	s_add_u32 s42, s42, 0x4000
	s_addc_u32 s43, s43, 0
	s_mov_b32 m0, s79
	v_lshl_add_u64 v[220:221], s[42:43], 0, v[178:179]
	ds_read_b128 v[162:165], v201 offset:32768
	ds_read_b128 v[166:169], v201 offset:33792
	ds_read_b128 v[170:173], v201 offset:34816
	ds_read_b128 v[174:177], v201 offset:35840
	ds_read_b128 v[190:193], v201 offset:36864
	ds_read_b128 v[202:205], v201 offset:37888
	ds_read_b128 v[206:209], v201 offset:38912
	ds_read_b128 v[210:213], v201 offset:39936
	global_load_lds_dwordx4 v[220:221], off
	s_mov_b32 m0, s87
	v_lshl_add_u64 v[220:221], s[42:43], 0, v[180:181]
	global_load_lds_dwordx4 v[220:221], off
	s_setprio 1
	s_waitcnt vmcnt(8) lgkmcnt(0)
	s_barrier
	v_mfma_f32_16x16x32_bf16 v[126:129], v[130:133], v[162:165], v[126:129]
	v_mfma_f32_16x16x32_bf16 v[122:125], v[138:141], v[162:165], v[122:125]
	v_mfma_f32_16x16x32_bf16 v[118:121], v[130:133], v[170:173], v[118:121]
	v_mfma_f32_16x16x32_bf16 v[114:117], v[138:141], v[170:173], v[114:117]
	v_mfma_f32_16x16x32_bf16 v[110:113], v[130:133], v[190:193], v[110:113]
	v_mfma_f32_16x16x32_bf16 v[102:105], v[138:141], v[190:193], v[102:105]
	v_mfma_f32_16x16x32_bf16 v[90:93], v[130:133], v[206:209], v[90:93]
	v_mfma_f32_16x16x32_bf16 v[82:85], v[138:141], v[206:209], v[82:85]
	v_mfma_f32_16x16x32_bf16 v[126:129], v[134:137], v[166:169], v[126:129]
	v_mfma_f32_16x16x32_bf16 v[122:125], v[142:145], v[166:169], v[122:125]
	v_mfma_f32_16x16x32_bf16 v[118:121], v[134:137], v[174:177], v[118:121]
	v_mfma_f32_16x16x32_bf16 v[114:117], v[142:145], v[174:177], v[114:117]
	v_mfma_f32_16x16x32_bf16 v[110:113], v[134:137], v[202:205], v[110:113]
	v_mfma_f32_16x16x32_bf16 v[102:105], v[142:145], v[202:205], v[102:105]
	v_mfma_f32_16x16x32_bf16 v[90:93], v[134:137], v[210:213], v[90:93]
	v_mfma_f32_16x16x32_bf16 v[82:85], v[142:145], v[210:213], v[82:85]
	v_mfma_f32_16x16x32_bf16 v[106:109], v[146:149], v[162:165], v[106:109]
	v_mfma_f32_16x16x32_bf16 v[98:101], v[154:157], v[162:165], v[98:101]
	v_mfma_f32_16x16x32_bf16 v[94:97], v[146:149], v[170:173], v[94:97]
	v_mfma_f32_16x16x32_bf16 v[86:89], v[154:157], v[170:173], v[86:89]
	v_mfma_f32_16x16x32_bf16 v[70:73], v[146:149], v[190:193], v[70:73]
	v_mfma_f32_16x16x32_bf16 v[62:65], v[154:157], v[190:193], v[62:65]
	v_mfma_f32_16x16x32_bf16 v[78:81], v[146:149], v[206:209], v[78:81]
	v_mfma_f32_16x16x32_bf16 v[66:69], v[154:157], v[206:209], v[66:69]
	v_mfma_f32_16x16x32_bf16 v[106:109], v[150:153], v[166:169], v[106:109]
	v_mfma_f32_16x16x32_bf16 v[98:101], v[158:161], v[166:169], v[98:101]
	v_mfma_f32_16x16x32_bf16 v[94:97], v[150:153], v[174:177], v[94:97]
	v_mfma_f32_16x16x32_bf16 v[86:89], v[158:161], v[174:177], v[86:89]
	v_mfma_f32_16x16x32_bf16 v[70:73], v[150:153], v[202:205], v[70:73]
	v_mfma_f32_16x16x32_bf16 v[62:65], v[158:161], v[202:205], v[62:65]
	v_mfma_f32_16x16x32_bf16 v[78:81], v[150:153], v[210:213], v[78:81]
	s_setprio 0
	v_mfma_f32_16x16x32_bf16 v[66:69], v[158:161], v[210:213], v[66:69]
	s_barrier
	s_add_i32 s34, s34, s91
	v_lshl_add_u64 v[194:195], v[194:195], 0, s[74:75]
	s_mov_b32 m0, s34
	ds_read_b128 v[162:165], v201 offset:49152
	ds_read_b128 v[166:169], v201 offset:50176
	ds_read_b128 v[170:173], v201 offset:51200
	ds_read_b128 v[174:177], v201 offset:52224
	ds_read_b128 v[190:193], v201 offset:53248
	ds_read_b128 v[202:205], v201 offset:54272
	ds_read_b128 v[206:209], v201 offset:55296
	ds_read_b128 v[210:213], v201 offset:56320
	global_load_lds_dwordx4 v[194:195], off
	s_add_i32 m0, s34, 0x2000
	s_add_u32 s6, s6, 0x80080
	v_lshl_add_u64 v[194:195], v[214:215], 0, s[74:75]
	s_addc_u32 s7, s7, 0
	s_add_i32 s34, s35, s91
	global_load_lds_dwordx4 v[194:195], off
	s_mov_b32 m0, s34
	v_lshl_add_u64 v[194:195], s[6:7], 0, v[0:1]
	global_load_lds_dwordx4 v[194:195], off
	s_add_i32 m0, s34, 0x2000
	v_lshl_add_u64 v[194:195], s[6:7], 0, v[182:183]
	global_load_lds_dwordx4 v[194:195], off
	s_mov_b32 m0, s67
	v_lshl_add_u64 v[194:195], v[216:217], 0, s[74:75]
	global_load_lds_dwordx4 v[194:195], off
	s_mov_b32 m0, s85
	v_lshl_add_u64 v[194:195], v[218:219], 0, s[74:75]
	global_load_lds_dwordx4 v[194:195], off
	s_setprio 1
	s_waitcnt vmcnt(8) lgkmcnt(0)
	s_barrier
	v_mfma_f32_16x16x32_bf16 v[54:57], v[130:133], v[162:165], v[54:57]
	v_mfma_f32_16x16x32_bf16 v[46:49], v[138:141], v[162:165], v[46:49]
	v_mfma_f32_16x16x32_bf16 v[38:41], v[130:133], v[170:173], v[38:41]
	v_mfma_f32_16x16x32_bf16 v[50:53], v[138:141], v[170:173], v[50:53]
	v_mfma_f32_16x16x32_bf16 v[18:21], v[130:133], v[190:193], v[18:21]
	v_mfma_f32_16x16x32_bf16 v[34:37], v[138:141], v[190:193], v[34:37]
	v_mfma_f32_16x16x32_bf16 v[22:25], v[130:133], v[206:209], v[22:25]
	v_mfma_f32_16x16x32_bf16 v[74:77], v[138:141], v[206:209], v[74:77]
	v_mfma_f32_16x16x32_bf16 v[54:57], v[134:137], v[166:169], v[54:57]
	v_mfma_f32_16x16x32_bf16 v[46:49], v[142:145], v[166:169], v[46:49]
	v_mfma_f32_16x16x32_bf16 v[38:41], v[134:137], v[174:177], v[38:41]
	v_mfma_f32_16x16x32_bf16 v[50:53], v[142:145], v[174:177], v[50:53]
	v_mfma_f32_16x16x32_bf16 v[18:21], v[134:137], v[202:205], v[18:21]
	v_mfma_f32_16x16x32_bf16 v[34:37], v[142:145], v[202:205], v[34:37]
	v_mfma_f32_16x16x32_bf16 v[22:25], v[134:137], v[210:213], v[22:25]
	v_mfma_f32_16x16x32_bf16 v[74:77], v[142:145], v[210:213], v[74:77]
	v_mfma_f32_16x16x32_bf16 v[58:61], v[146:149], v[162:165], v[58:61]
	v_mfma_f32_16x16x32_bf16 v[30:33], v[154:157], v[162:165], v[30:33]
	v_mfma_f32_16x16x32_bf16 v[42:45], v[146:149], v[170:173], v[42:45]
	v_mfma_f32_16x16x32_bf16 v[6:9], v[154:157], v[170:173], v[6:9]
	v_mfma_f32_16x16x32_bf16 v[26:29], v[146:149], v[190:193], v[26:29]
	v_mfma_f32_16x16x32_bf16 v[10:13], v[154:157], v[190:193], v[10:13]
	v_mfma_f32_16x16x32_bf16 v[14:17], v[146:149], v[206:209], v[14:17]
	v_mfma_f32_16x16x32_bf16 v[2:5], v[154:157], v[206:209], v[2:5]
	v_mfma_f32_16x16x32_bf16 v[58:61], v[150:153], v[166:169], v[58:61]
	v_mfma_f32_16x16x32_bf16 v[30:33], v[158:161], v[166:169], v[30:33]
	v_mfma_f32_16x16x32_bf16 v[42:45], v[150:153], v[174:177], v[42:45]
	v_mfma_f32_16x16x32_bf16 v[6:9], v[158:161], v[174:177], v[6:9]
	v_mfma_f32_16x16x32_bf16 v[26:29], v[150:153], v[202:205], v[26:29]
	v_mfma_f32_16x16x32_bf16 v[10:13], v[158:161], v[202:205], v[10:13]
	v_mfma_f32_16x16x32_bf16 v[14:17], v[150:153], v[210:213], v[14:17]
	s_setprio 0
	v_mfma_f32_16x16x32_bf16 v[2:5], v[158:161], v[210:213], v[2:5]
	s_barrier
	s_add_i32 s31, s31, 2
	s_add_u32 s29, s29, 0x100
	s_addc_u32 s30, s30, 0
	s_cmp_gt_u32 s31, 29
	s_mov_b64 s[44:45], s[4:5]
; #define PG8_STAGE(bufoff, gbase, voff) do { _Pragma("unroll") for (int _i = 0; _i < 2; ++_i) \
;         __builtin_amdgcn_global_load_lds((const unsigned*)((const char*)(gbase) + (voff)[_i]), (LAS unsigned*)(lds + (bufoff) + ldsw + _i * 8192), 16, 0, 0); } while (0)
; #define PG8_LDA(dst, b, h) do { _Pragma("unroll") for (int m = 0; m < 4; ++m) _Pragma("unroll") for (int k = 0; k < 2; ++k) dst[m][k] = *(const LAS bf16x8*)(lds + PG8_SA(b, h) + aoff + m * 2048 + k * 1024); } while (0)
; #define PG8_LDB(dst, b, h) do { _Pragma("unroll") for (int n = 0; n < 2; ++n) _Pragma("unroll") for (int k = 0; k < 2; ++k) dst[n][k] = *(const LAS bf16x8*)(lds + PG8_SB(b, h) + boff + n * 2048 + k * 1024); } while (0)
; #define PG8_MMA(ai, bj, At, Bt) do { __builtin_amdgcn_s_setprio(1); _Pragma("unroll") for (int m = 0; m < 4; ++m) _Pragma("unroll") for (int n = 0; n < 2; ++n) _Pragma("unroll") for (int k = 0; k < 2; ++k) \
;         acc[ai][bj][m][n] = __builtin_amdgcn_mfma_f32_16x16x32_bf16(Bt[n][k], At[m][k], acc[ai][bj][m][n], 0, 0, 0); __builtin_amdgcn_s_setprio(0); } while (0)
; #define PG8_WAIT_V(n) asm volatile("s_waitcnt vmcnt(" #n ")" ::: "memory")
; #define PG8_WAIT_L(n) asm volatile("s_waitcnt lgkmcnt(" #n ")" ::: "memory")
; #define PG8_BAR __builtin_amdgcn_s_barrier()
; #define PG8_SCHED __builtin_amdgcn_sched_barrier(0)
; template <class Epi, int AMODE>
; __device__ __forceinline__ void gemm_phase(LAS unsigned char* lds, const Gemm g, const StaticOrder& S, const Epi& E, int stagger_us, int tid_in) {
;     ...
;             const bool last = (t == nt - 2);
;             const char* a1 = cA + (size_t)(t + 1) * kstep;
;             const char* a2 = last ? nA : cA + (size_t)(t + 2) * kstep; const char* b2 = last ? nB : cB + (size_t)(t + 2) * kstep;
;             const char* a3 = a2 + kstep; const char* b3 = b2 + kstep;
;             PG8_LDB(B0, 0, 0); PG8_LDB(B1, 0, 1); PG8_SCHED; PG8_LDA(At, 0, 0); PG8_STAGE(PG8_SA(1, 1), a1 + hstepA, voffA);
;             PG8_WAIT_V(8); PG8_WAIT_L(0); PG8_BAR; PG8_MMA(0, 0, At, B0); PG8_MMA(0, 1, At, B1); PG8_BAR; PG8_SCHED;
;             PG8_LDA(At, 0, 1); PG8_STAGE(PG8_SB(0, 0), b2, voffB); PG8_STAGE(PG8_SB(0, 1), b2 + hstepB, voffB); PG8_STAGE(PG8_SA(0, 0), a2, voffA);
.LBB0_1299:
	s_add_u32 s4, s44, 0x100
	s_addc_u32 s5, s45, 0
	s_add_i32 s34, 0, 0x10000
	s_cmp_eq_u32 s31, 28
	s_cselect_b32 s43, s95, s5
	s_cselect_b32 s42, s94, s4
	s_cselect_b32 s7, s27, s30
	s_cselect_b32 s6, s28, s29
	s_add_i32 s35, 0, 0x14000
	v_add_u32_e32 v142, s34, v196
	v_add_u32_e32 v158, s35, v196
	ds_read_b128 v[130:133], v142
	ds_read_b128 v[134:137], v142 offset:1024
	ds_read_b128 v[138:141], v142 offset:2048
	ds_read_b128 v[142:145], v142 offset:3072
	ds_read_b128 v[146:149], v158
	ds_read_b128 v[150:153], v158 offset:1024
	ds_read_b128 v[154:157], v158 offset:2048
	ds_read_b128 v[158:161], v158 offset:3072
	v_lshl_add_u64 v[194:195], s[44:45], 0, v[186:187]
	s_add_i32 m0, s93, 0xc000
	ds_read_b128 v[162:165], v201
	ds_read_b128 v[166:169], v201 offset:1024
	ds_read_b128 v[170:173], v201 offset:2048
	ds_read_b128 v[174:177], v201 offset:3072
	ds_read_b128 v[190:193], v201 offset:4096
	ds_read_b128 v[202:205], v201 offset:5120
	ds_read_b128 v[206:209], v201 offset:6144
	ds_read_b128 v[210:213], v201 offset:7168
	global_load_lds_dwordx4 v[194:195], off
	s_add_i32 m0, s93, 0xe000
	v_lshl_add_u64 v[194:195], s[44:45], 0, v[188:189]
	global_load_lds_dwordx4 v[194:195], off
	s_setprio 1
	s_waitcnt vmcnt(8) lgkmcnt(0)
	s_barrier
	v_mfma_f32_16x16x32_bf16 v[126:129], v[130:133], v[162:165], v[126:129]
	v_mfma_f32_16x16x32_bf16 v[122:125], v[138:141], v[162:165], v[122:125]
	v_mfma_f32_16x16x32_bf16 v[118:121], v[130:133], v[170:173], v[118:121]
	v_mfma_f32_16x16x32_bf16 v[114:117], v[138:141], v[170:173], v[114:117]
	v_mfma_f32_16x16x32_bf16 v[110:113], v[130:133], v[190:193], v[110:113]
	v_mfma_f32_16x16x32_bf16 v[102:105], v[138:141], v[190:193], v[102:105]
	v_mfma_f32_16x16x32_bf16 v[90:93], v[130:133], v[206:209], v[90:93]
	v_mfma_f32_16x16x32_bf16 v[82:85], v[138:141], v[206:209], v[82:85]
	v_mfma_f32_16x16x32_bf16 v[126:129], v[134:137], v[166:169], v[126:129]
	v_mfma_f32_16x16x32_bf16 v[122:125], v[142:145], v[166:169], v[122:125]
	v_mfma_f32_16x16x32_bf16 v[118:121], v[134:137], v[174:177], v[118:121]
	v_mfma_f32_16x16x32_bf16 v[114:117], v[142:145], v[174:177], v[114:117]
	v_mfma_f32_16x16x32_bf16 v[110:113], v[134:137], v[202:205], v[110:113]
	v_mfma_f32_16x16x32_bf16 v[102:105], v[142:145], v[202:205], v[102:105]
	v_mfma_f32_16x16x32_bf16 v[90:93], v[134:137], v[210:213], v[90:93]
	v_mfma_f32_16x16x32_bf16 v[82:85], v[142:145], v[210:213], v[82:85]
	v_mfma_f32_16x16x32_bf16 v[106:109], v[146:149], v[162:165], v[106:109]
	v_mfma_f32_16x16x32_bf16 v[98:101], v[154:157], v[162:165], v[98:101]
	v_mfma_f32_16x16x32_bf16 v[94:97], v[146:149], v[170:173], v[94:97]
	v_mfma_f32_16x16x32_bf16 v[86:89], v[154:157], v[170:173], v[86:89]
	v_mfma_f32_16x16x32_bf16 v[70:73], v[146:149], v[190:193], v[70:73]
	v_mfma_f32_16x16x32_bf16 v[62:65], v[154:157], v[190:193], v[62:65]
	v_mfma_f32_16x16x32_bf16 v[78:81], v[146:149], v[206:209], v[78:81]
	v_mfma_f32_16x16x32_bf16 v[66:69], v[154:157], v[206:209], v[66:69]
	v_mfma_f32_16x16x32_bf16 v[106:109], v[150:153], v[166:169], v[106:109]
	v_mfma_f32_16x16x32_bf16 v[98:101], v[158:161], v[166:169], v[98:101]
	v_mfma_f32_16x16x32_bf16 v[94:97], v[150:153], v[174:177], v[94:97]
	v_mfma_f32_16x16x32_bf16 v[86:89], v[158:161], v[174:177], v[86:89]
	v_mfma_f32_16x16x32_bf16 v[70:73], v[150:153], v[202:205], v[70:73]
	v_mfma_f32_16x16x32_bf16 v[62:65], v[158:161], v[202:205], v[62:65]
	v_mfma_f32_16x16x32_bf16 v[78:81], v[150:153], v[210:213], v[78:81]
	s_setprio 0
	v_mfma_f32_16x16x32_bf16 v[66:69], v[158:161], v[210:213], v[66:69]
	s_barrier
	s_add_i32 s34, s34, s91
	v_lshl_add_u64 v[194:195], s[6:7], 0, v[0:1]
	s_mov_b32 m0, s34
	ds_read_b128 v[162:165], v201 offset:16384
	ds_read_b128 v[166:169], v201 offset:17408
	ds_read_b128 v[170:173], v201 offset:18432
	ds_read_b128 v[174:177], v201 offset:19456
	ds_read_b128 v[190:193], v201 offset:20480
	ds_read_b128 v[202:205], v201 offset:21504
	ds_read_b128 v[206:209], v201 offset:22528
	ds_read_b128 v[210:213], v201 offset:23552
	global_load_lds_dwordx4 v[194:195], off
	s_add_i32 m0, s34, 0x2000
	s_add_u32 s44, s6, 0x80000
	v_lshl_add_u64 v[214:215], s[6:7], 0, v[182:183]
	s_addc_u32 s45, s7, 0
	s_add_i32 s34, s35, s91
	global_load_lds_dwordx4 v[214:215], off
	v_lshl_add_u64 v[216:217], s[44:45], 0, v[0:1]
	s_mov_b32 m0, s34
	v_lshl_add_u64 v[218:219], s[42:43], 0, v[180:181]
	global_load_lds_dwordx4 v[216:217], off
	s_add_i32 m0, s34, 0x2000
	v_lshl_add_u64 v[216:217], s[44:45], 0, v[182:183]
	global_load_lds_dwordx4 v[216:217], off
	s_mov_b32 m0, s93
	v_lshl_add_u64 v[216:217], s[42:43], 0, v[178:179]
	global_load_lds_dwordx4 v[216:217], off
	s_mov_b32 m0, s83
	s_nop 0
	global_load_lds_dwordx4 v[218:219], off
	s_setprio 1
	s_waitcnt vmcnt(8) lgkmcnt(0)
	s_barrier
; #define PG8_STAGE(bufoff, gbase, voff) do { _Pragma("unroll") for (int _i = 0; _i < 2; ++_i) \
;         __builtin_amdgcn_global_load_lds((const unsigned*)((const char*)(gbase) + (voff)[_i]), (LAS unsigned*)(lds + (bufoff) + ldsw + _i * 8192), 16, 0, 0); } while (0)
; #define PG8_LDA(dst, b, h) do { _Pragma("unroll") for (int m = 0; m < 4; ++m) _Pragma("unroll") for (int k = 0; k < 2; ++k) dst[m][k] = *(const LAS bf16x8*)(lds + PG8_SA(b, h) + aoff + m * 2048 + k * 1024); } while (0)
; #define PG8_LDB(dst, b, h) do { _Pragma("unroll") for (int n = 0; n < 2; ++n) _Pragma("unroll") for (int k = 0; k < 2; ++k) dst[n][k] = *(const LAS bf16x8*)(lds + PG8_SB(b, h) + boff + n * 2048 + k * 1024); } while (0)
; #define PG8_MMA(ai, bj, At, Bt) do { __builtin_amdgcn_s_setprio(1); _Pragma("unroll") for (int m = 0; m < 4; ++m) _Pragma("unroll") for (int n = 0; n < 2; ++n) _Pragma("unroll") for (int k = 0; k < 2; ++k) \
;         acc[ai][bj][m][n] = __builtin_amdgcn_mfma_f32_16x16x32_bf16(Bt[n][k], At[m][k], acc[ai][bj][m][n], 0, 0, 0); __builtin_amdgcn_s_setprio(0); } while (0)
; #define PG8_WAIT_V(n) asm volatile("s_waitcnt vmcnt(" #n ")" ::: "memory")
; #define PG8_WAIT_L(n) asm volatile("s_waitcnt lgkmcnt(" #n ")" ::: "memory")
; #define PG8_BAR __builtin_amdgcn_s_barrier()
; #define PG8_SCHED __builtin_amdgcn_sched_barrier(0)
; template <class Epi, int AMODE>
; __device__ __forceinline__ void gemm_phase(LAS unsigned char* lds, const Gemm g, const StaticOrder& S, const Epi& E, int stagger_us, int tid_in) {
;     ...
;             PG8_WAIT_V(8); PG8_WAIT_L(0); PG8_BAR; PG8_MMA(1, 0, At, B0); PG8_MMA(1, 1, At, B1); PG8_BAR; PG8_SCHED;
;             PG8_LDB(B0, 1, 0); PG8_LDB(B1, 1, 1); PG8_SCHED; PG8_LDA(At, 1, 0); PG8_STAGE(PG8_SA(0, 1), a2 + hstepA, voffA);
;             PG8_WAIT_V(8); PG8_WAIT_L(0); PG8_BAR; PG8_MMA(0, 0, At, B0); PG8_MMA(0, 1, At, B1); PG8_BAR; PG8_SCHED;
	v_mfma_f32_16x16x32_bf16 v[54:57], v[130:133], v[162:165], v[54:57]
	v_mfma_f32_16x16x32_bf16 v[46:49], v[138:141], v[162:165], v[46:49]
	v_mfma_f32_16x16x32_bf16 v[38:41], v[130:133], v[170:173], v[38:41]
	v_mfma_f32_16x16x32_bf16 v[50:53], v[138:141], v[170:173], v[50:53]
	v_mfma_f32_16x16x32_bf16 v[18:21], v[130:133], v[190:193], v[18:21]
	v_mfma_f32_16x16x32_bf16 v[34:37], v[138:141], v[190:193], v[34:37]
	v_mfma_f32_16x16x32_bf16 v[22:25], v[130:133], v[206:209], v[22:25]
	v_mfma_f32_16x16x32_bf16 v[74:77], v[138:141], v[206:209], v[74:77]
	v_mfma_f32_16x16x32_bf16 v[54:57], v[134:137], v[166:169], v[54:57]
	v_mfma_f32_16x16x32_bf16 v[46:49], v[142:145], v[166:169], v[46:49]
	v_mfma_f32_16x16x32_bf16 v[38:41], v[134:137], v[174:177], v[38:41]
	v_mfma_f32_16x16x32_bf16 v[50:53], v[142:145], v[174:177], v[50:53]
	v_mfma_f32_16x16x32_bf16 v[18:21], v[134:137], v[202:205], v[18:21]
	v_mfma_f32_16x16x32_bf16 v[34:37], v[142:145], v[202:205], v[34:37]
	v_mfma_f32_16x16x32_bf16 v[22:25], v[134:137], v[210:213], v[22:25]
	v_mfma_f32_16x16x32_bf16 v[74:77], v[142:145], v[210:213], v[74:77]
	v_mfma_f32_16x16x32_bf16 v[58:61], v[146:149], v[162:165], v[58:61]
	v_mfma_f32_16x16x32_bf16 v[30:33], v[154:157], v[162:165], v[30:33]
	v_mfma_f32_16x16x32_bf16 v[42:45], v[146:149], v[170:173], v[42:45]
	v_mfma_f32_16x16x32_bf16 v[6:9], v[154:157], v[170:173], v[6:9]
	v_mfma_f32_16x16x32_bf16 v[26:29], v[146:149], v[190:193], v[26:29]
	v_mfma_f32_16x16x32_bf16 v[10:13], v[154:157], v[190:193], v[10:13]
	v_mfma_f32_16x16x32_bf16 v[14:17], v[146:149], v[206:209], v[14:17]
	v_mfma_f32_16x16x32_bf16 v[2:5], v[154:157], v[206:209], v[2:5]
	v_mfma_f32_16x16x32_bf16 v[58:61], v[150:153], v[166:169], v[58:61]
	v_mfma_f32_16x16x32_bf16 v[30:33], v[158:161], v[166:169], v[30:33]
	v_mfma_f32_16x16x32_bf16 v[42:45], v[150:153], v[174:177], v[42:45]
	v_mfma_f32_16x16x32_bf16 v[6:9], v[158:161], v[174:177], v[6:9]
	v_mfma_f32_16x16x32_bf16 v[26:29], v[150:153], v[202:205], v[26:29]
	v_mfma_f32_16x16x32_bf16 v[10:13], v[158:161], v[202:205], v[10:13]
	v_mfma_f32_16x16x32_bf16 v[14:17], v[150:153], v[210:213], v[14:17]
	s_setprio 0
	v_mfma_f32_16x16x32_bf16 v[2:5], v[158:161], v[210:213], v[2:5]
	s_barrier
	s_add_i32 s34, 0, 0x18000
	s_add_i32 s35, 0, 0x1c000
	v_add_u32_e32 v142, s34, v196
	v_add_u32_e32 v158, s35, v196
	ds_read_b128 v[130:133], v142
	ds_read_b128 v[134:137], v142 offset:1024
	ds_read_b128 v[138:141], v142 offset:2048
	ds_read_b128 v[142:145], v142 offset:3072
	ds_read_b128 v[146:149], v158
	ds_read_b128 v[150:153], v158 offset:1024
	ds_read_b128 v[154:157], v158 offset:2048
	ds_read_b128 v[158:161], v158 offset:3072
	s_add_u32 s42, s42, 0x4000
	s_addc_u32 s43, s43, 0
	s_mov_b32 m0, s79
	v_lshl_add_u64 v[220:221], s[42:43], 0, v[178:179]
	ds_read_b128 v[162:165], v201 offset:32768
	ds_read_b128 v[166:169], v201 offset:33792
	ds_read_b128 v[170:173], v201 offset:34816
	ds_read_b128 v[174:177], v201 offset:35840
	ds_read_b128 v[190:193], v201 offset:36864
	ds_read_b128 v[202:205], v201 offset:37888
	ds_read_b128 v[206:209], v201 offset:38912
	ds_read_b128 v[210:213], v201 offset:39936
	global_load_lds_dwordx4 v[220:221], off
	s_mov_b32 m0, s87
	v_lshl_add_u64 v[220:221], s[42:43], 0, v[180:181]
	global_load_lds_dwordx4 v[220:221], off
	s_setprio 1
	s_waitcnt vmcnt(8) lgkmcnt(0)
	s_barrier
	v_mfma_f32_16x16x32_bf16 v[126:129], v[130:133], v[162:165], v[126:129]
	v_mfma_f32_16x16x32_bf16 v[122:125], v[138:141], v[162:165], v[122:125]
	v_mfma_f32_16x16x32_bf16 v[118:121], v[130:133], v[170:173], v[118:121]
	v_mfma_f32_16x16x32_bf16 v[114:117], v[138:141], v[170:173], v[114:117]
	v_mfma_f32_16x16x32_bf16 v[110:113], v[130:133], v[190:193], v[110:113]
	v_mfma_f32_16x16x32_bf16 v[102:105], v[138:141], v[190:193], v[102:105]
	v_mfma_f32_16x16x32_bf16 v[90:93], v[130:133], v[206:209], v[90:93]
	v_mfma_f32_16x16x32_bf16 v[82:85], v[138:141], v[206:209], v[82:85]
	v_mfma_f32_16x16x32_bf16 v[126:129], v[134:137], v[166:169], v[126:129]
	v_mfma_f32_16x16x32_bf16 v[122:125], v[142:145], v[166:169], v[122:125]
	v_mfma_f32_16x16x32_bf16 v[118:121], v[134:137], v[174:177], v[118:121]
	v_mfma_f32_16x16x32_bf16 v[114:117], v[142:145], v[174:177], v[114:117]
	v_mfma_f32_16x16x32_bf16 v[110:113], v[134:137], v[202:205], v[110:113]
	v_mfma_f32_16x16x32_bf16 v[102:105], v[142:145], v[202:205], v[102:105]
	v_mfma_f32_16x16x32_bf16 v[90:93], v[134:137], v[210:213], v[90:93]
	v_mfma_f32_16x16x32_bf16 v[82:85], v[142:145], v[210:213], v[82:85]
	v_mfma_f32_16x16x32_bf16 v[106:109], v[146:149], v[162:165], v[106:109]
	v_mfma_f32_16x16x32_bf16 v[98:101], v[154:157], v[162:165], v[98:101]
	v_mfma_f32_16x16x32_bf16 v[94:97], v[146:149], v[170:173], v[94:97]
	v_mfma_f32_16x16x32_bf16 v[86:89], v[154:157], v[170:173], v[86:89]
	v_mfma_f32_16x16x32_bf16 v[70:73], v[146:149], v[190:193], v[70:73]
	v_mfma_f32_16x16x32_bf16 v[62:65], v[154:157], v[190:193], v[62:65]
	v_mfma_f32_16x16x32_bf16 v[78:81], v[146:149], v[206:209], v[78:81]
	v_mfma_f32_16x16x32_bf16 v[66:69], v[154:157], v[206:209], v[66:69]
	v_mfma_f32_16x16x32_bf16 v[106:109], v[150:153], v[166:169], v[106:109]
	v_mfma_f32_16x16x32_bf16 v[98:101], v[158:161], v[166:169], v[98:101]
	v_mfma_f32_16x16x32_bf16 v[94:97], v[150:153], v[174:177], v[94:97]
	v_mfma_f32_16x16x32_bf16 v[86:89], v[158:161], v[174:177], v[86:89]
	v_mfma_f32_16x16x32_bf16 v[70:73], v[150:153], v[202:205], v[70:73]
	v_mfma_f32_16x16x32_bf16 v[62:65], v[158:161], v[202:205], v[62:65]
	v_mfma_f32_16x16x32_bf16 v[78:81], v[150:153], v[210:213], v[78:81]
	s_setprio 0
	v_mfma_f32_16x16x32_bf16 v[66:69], v[158:161], v[210:213], v[66:69]
	s_barrier
; #define PG8_STAGE(bufoff, gbase, voff) do { _Pragma("unroll") for (int _i = 0; _i < 2; ++_i) \
;         __builtin_amdgcn_global_load_lds((const unsigned*)((const char*)(gbase) + (voff)[_i]), (LAS unsigned*)(lds + (bufoff) + ldsw + _i * 8192), 16, 0, 0); } while (0)
; #define PG8_LDA(dst, b, h) do { _Pragma("unroll") for (int m = 0; m < 4; ++m) _Pragma("unroll") for (int k = 0; k < 2; ++k) dst[m][k] = *(const LAS bf16x8*)(lds + PG8_SA(b, h) + aoff + m * 2048 + k * 1024); } while (0)
; #define PG8_MMA(ai, bj, At, Bt) do { __builtin_amdgcn_s_setprio(1); _Pragma("unroll") for (int m = 0; m < 4; ++m) _Pragma("unroll") for (int n = 0; n < 2; ++n) _Pragma("unroll") for (int k = 0; k < 2; ++k) \
;         acc[ai][bj][m][n] = __builtin_amdgcn_mfma_f32_16x16x32_bf16(Bt[n][k], At[m][k], acc[ai][bj][m][n], 0, 0, 0); __builtin_amdgcn_s_setprio(0); } while (0)
; #define PG8_WAIT_V(n) asm volatile("s_waitcnt vmcnt(" #n ")" ::: "memory")
; #define PG8_WAIT_L(n) asm volatile("s_waitcnt lgkmcnt(" #n ")" ::: "memory")
; #define PG8_BAR __builtin_amdgcn_s_barrier()
; #define PG8_SCHED __builtin_amdgcn_sched_barrier(0)
; template <class Epi, int AMODE>
; __device__ __forceinline__ void gemm_phase(LAS unsigned char* lds, const Gemm g, const StaticOrder& S, const Epi& E, int stagger_us, int tid_in) {
;     ...
;             PG8_LDA(At, 1, 1); PG8_STAGE(PG8_SB(1, 0), b3, voffB); PG8_STAGE(PG8_SB(1, 1), b3 + hstepB, voffB); PG8_STAGE(PG8_SA(1, 0), a3, voffA);
;             PG8_WAIT_V(8); PG8_WAIT_L(0); PG8_BAR; PG8_MMA(1, 0, At, B0); PG8_MMA(1, 1, At, B1); PG8_BAR; PG8_SCHED;
;         }
;         if (wr == 0) PG8_BAR;
	s_add_i32 s34, s34, s91
	v_lshl_add_u64 v[194:195], v[194:195], 0, s[74:75]
	s_mov_b32 m0, s34
	ds_read_b128 v[162:165], v201 offset:49152
	ds_read_b128 v[166:169], v201 offset:50176
	ds_read_b128 v[170:173], v201 offset:51200
	ds_read_b128 v[174:177], v201 offset:52224
	ds_read_b128 v[190:193], v201 offset:53248
	ds_read_b128 v[202:205], v201 offset:54272
	ds_read_b128 v[206:209], v201 offset:55296
	ds_read_b128 v[210:213], v201 offset:56320
	global_load_lds_dwordx4 v[194:195], off
	s_add_i32 m0, s34, 0x2000
	s_add_u32 s6, s6, 0x80080
	v_lshl_add_u64 v[194:195], v[214:215], 0, s[74:75]
	s_addc_u32 s7, s7, 0
	s_add_i32 s34, s35, s91
	global_load_lds_dwordx4 v[194:195], off
	s_mov_b32 m0, s34
	v_lshl_add_u64 v[194:195], s[6:7], 0, v[0:1]
	global_load_lds_dwordx4 v[194:195], off
	s_add_i32 m0, s34, 0x2000
	v_lshl_add_u64 v[194:195], s[6:7], 0, v[182:183]
	global_load_lds_dwordx4 v[194:195], off
	s_mov_b32 m0, s67
	v_lshl_add_u64 v[194:195], v[216:217], 0, s[74:75]
	global_load_lds_dwordx4 v[194:195], off
	s_mov_b32 m0, s85
	v_lshl_add_u64 v[194:195], v[218:219], 0, s[74:75]
	global_load_lds_dwordx4 v[194:195], off
	s_setprio 1
	s_waitcnt vmcnt(8) lgkmcnt(0)
	s_barrier
	v_mfma_f32_16x16x32_bf16 v[54:57], v[130:133], v[162:165], v[54:57]
	v_mfma_f32_16x16x32_bf16 v[46:49], v[138:141], v[162:165], v[46:49]
	v_mfma_f32_16x16x32_bf16 v[38:41], v[130:133], v[170:173], v[38:41]
	v_mfma_f32_16x16x32_bf16 v[50:53], v[138:141], v[170:173], v[50:53]
	v_mfma_f32_16x16x32_bf16 v[18:21], v[130:133], v[190:193], v[18:21]
	v_mfma_f32_16x16x32_bf16 v[34:37], v[138:141], v[190:193], v[34:37]
	v_mfma_f32_16x16x32_bf16 v[22:25], v[130:133], v[206:209], v[22:25]
	v_mfma_f32_16x16x32_bf16 v[74:77], v[138:141], v[206:209], v[74:77]
	v_mfma_f32_16x16x32_bf16 v[54:57], v[134:137], v[166:169], v[54:57]
	v_mfma_f32_16x16x32_bf16 v[46:49], v[142:145], v[166:169], v[46:49]
	v_mfma_f32_16x16x32_bf16 v[38:41], v[134:137], v[174:177], v[38:41]
	v_mfma_f32_16x16x32_bf16 v[50:53], v[142:145], v[174:177], v[50:53]
	v_mfma_f32_16x16x32_bf16 v[18:21], v[134:137], v[202:205], v[18:21]
	v_mfma_f32_16x16x32_bf16 v[34:37], v[142:145], v[202:205], v[34:37]
	v_mfma_f32_16x16x32_bf16 v[22:25], v[134:137], v[210:213], v[22:25]
	v_mfma_f32_16x16x32_bf16 v[74:77], v[142:145], v[210:213], v[74:77]
	v_mfma_f32_16x16x32_bf16 v[58:61], v[146:149], v[162:165], v[58:61]
	v_mfma_f32_16x16x32_bf16 v[30:33], v[154:157], v[162:165], v[30:33]
	v_mfma_f32_16x16x32_bf16 v[42:45], v[146:149], v[170:173], v[42:45]
	v_mfma_f32_16x16x32_bf16 v[6:9], v[154:157], v[170:173], v[6:9]
	v_mfma_f32_16x16x32_bf16 v[26:29], v[146:149], v[190:193], v[26:29]
	v_mfma_f32_16x16x32_bf16 v[10:13], v[154:157], v[190:193], v[10:13]
	v_mfma_f32_16x16x32_bf16 v[14:17], v[146:149], v[206:209], v[14:17]
	v_mfma_f32_16x16x32_bf16 v[2:5], v[154:157], v[206:209], v[2:5]
	v_mfma_f32_16x16x32_bf16 v[58:61], v[150:153], v[166:169], v[58:61]
	v_mfma_f32_16x16x32_bf16 v[30:33], v[158:161], v[166:169], v[30:33]
	v_mfma_f32_16x16x32_bf16 v[42:45], v[150:153], v[174:177], v[42:45]
	v_mfma_f32_16x16x32_bf16 v[6:9], v[158:161], v[174:177], v[6:9]
	v_mfma_f32_16x16x32_bf16 v[26:29], v[150:153], v[202:205], v[26:29]
	v_mfma_f32_16x16x32_bf16 v[10:13], v[158:161], v[202:205], v[10:13]
	v_mfma_f32_16x16x32_bf16 v[14:17], v[150:153], v[210:213], v[14:17]
	s_setprio 0
	v_mfma_f32_16x16x32_bf16 v[2:5], v[158:161], v[210:213], v[2:5]
	s_barrier
	s_add_i32 s31, s31, 2
	s_add_u32 s29, s29, 0x100
	s_addc_u32 s30, s30, 0
	s_cmp_gt_u32 s31, 29
	s_mov_b64 s[44:45], s[4:5]
	s_cbranch_scc0 .LBB0_1299
	s_and_b64 vcc, exec, s[48:49]
	s_cbranch_vccz .LBB0_1302
	s_barrier

; #define PG8_STAGE(bufoff, gbase, voff) do { _Pragma("unroll") for (int _i = 0; _i < 2; ++_i) \
;         __builtin_amdgcn_global_load_lds((const unsigned*)((const char*)(gbase) + (voff)[_i]), (LAS unsigned*)(lds + (bufoff) + ldsw + _i * 8192), 16, 0, 0); } while (0)
; #define PG8_LDA(dst, b, h) do { _Pragma("unroll") for (int m = 0; m < 4; ++m) _Pragma("unroll") for (int k = 0; k < 2; ++k) dst[m][k] = *(const LAS bf16x8*)(lds + PG8_SA(b, h) + aoff + m * 2048 + k * 1024); } while (0)
; #define PG8_LDB(dst, b, h) do { _Pragma("unroll") for (int n = 0; n < 2; ++n) _Pragma("unroll") for (int k = 0; k < 2; ++k) dst[n][k] = *(const LAS bf16x8*)(lds + PG8_SB(b, h) + boff + n * 2048 + k * 1024); } while (0)
; #define PG8_MMA(ai, bj, At, Bt) do { __builtin_amdgcn_s_setprio(1); _Pragma("unroll") for (int m = 0; m < 4; ++m) _Pragma("unroll") for (int n = 0; n < 2; ++n) _Pragma("unroll") for (int k = 0; k < 2; ++k) \
;         acc[ai][bj][m][n] = __builtin_amdgcn_mfma_f32_16x16x32_bf16(Bt[n][k], At[m][k], acc[ai][bj][m][n], 0, 0, 0); __builtin_amdgcn_s_setprio(0); } while (0)
; #define PG8_WAIT_V(n) asm volatile("s_waitcnt vmcnt(" #n ")" ::: "memory")
; #define PG8_WAIT_L(n) asm volatile("s_waitcnt lgkmcnt(" #n ")" ::: "memory")
; #define PG8_BAR __builtin_amdgcn_s_barrier()
; #define PG8_SCHED __builtin_amdgcn_sched_barrier(0)
; template <class Epi, int AMODE>
; __device__ __forceinline__ void gemm_phase(LAS unsigned char* lds, const Gemm g, const StaticOrder& S, const Epi& E, int stagger_us, int tid_in) {
;     ...
;             const bool last = (t == nt - 2);
;             const char* a1 = cA + (size_t)(t + 1) * kstep;
;             const char* a2 = last ? nA : cA + (size_t)(t + 2) * kstep; const char* b2 = last ? nB : cB + (size_t)(t + 2) * kstep;
;             const char* a3 = a2 + kstep; const char* b3 = b2 + kstep;
;             PG8_LDB(B0, 0, 0); PG8_LDB(B1, 0, 1); PG8_SCHED; PG8_LDA(At, 0, 0); PG8_STAGE(PG8_SA(1, 1), a1 + hstepA, voffA);
;             PG8_WAIT_V(8); PG8_WAIT_L(0); PG8_BAR; PG8_MMA(0, 0, At, B0); PG8_MMA(0, 1, At, B1); PG8_BAR; PG8_SCHED;
;             PG8_LDA(At, 0, 1); PG8_STAGE(PG8_SB(0, 0), b2, voffB); PG8_STAGE(PG8_SB(0, 1), b2 + hstepB, voffB); PG8_STAGE(PG8_SA(0, 0), a2, voffA);
.LBB0_1476:
	s_add_u32 s4, s54, 0x100
	s_addc_u32 s5, s55, 0
	s_add_i32 s30, 0, 0x10000
	s_cmpk_eq_i32 s29, 0x52
	s_cselect_b32 s57, s41, s5
	s_cselect_b32 s56, s40, s4
	s_cselect_b32 s7, s53, s28
	s_cselect_b32 s6, s52, s27
	s_add_i32 s34, 0, 0x14000
	v_add_u32_e32 v102, s30, v162
	v_add_u32_e32 v165, s34, v162
	ds_read_b128 v[66:69], v102
	ds_read_b128 v[70:73], v102 offset:1024
	ds_read_b128 v[74:77], v102 offset:2048
	ds_read_b128 v[102:105], v102 offset:3072
	ds_read_b128 v[152:155], v165
	ds_read_b128 v[156:159], v165 offset:1024
	ds_read_b128 v[166:169], v165 offset:2048
	ds_read_b128 v[170:173], v165 offset:3072
	v_lshl_add_u64 v[206:207], s[54:55], 0, v[148:149]
	s_add_i32 m0, s13, 0xc000
	ds_read_b128 v[174:177], v164
	ds_read_b128 v[178:181], v164 offset:1024
	ds_read_b128 v[182:185], v164 offset:2048
	ds_read_b128 v[186:189], v164 offset:3072
	ds_read_b128 v[190:193], v164 offset:4096
	ds_read_b128 v[194:197], v164 offset:5120
	ds_read_b128 v[198:201], v164 offset:6144
	ds_read_b128 v[202:205], v164 offset:7168
	global_load_lds_dwordx4 v[206:207], off
	s_add_i32 m0, s13, 0xe000
	v_lshl_add_u64 v[206:207], s[54:55], 0, v[150:151]
	global_load_lds_dwordx4 v[206:207], off
	s_setprio 1
	s_waitcnt vmcnt(8) lgkmcnt(0)
	s_barrier
	v_mfma_f32_16x16x32_bf16 v[142:145], v[66:69], v[174:177], v[142:145]
	v_mfma_f32_16x16x32_bf16 v[138:141], v[74:77], v[174:177], v[138:141]
	v_mfma_f32_16x16x32_bf16 v[134:137], v[66:69], v[182:185], v[134:137]
	v_mfma_f32_16x16x32_bf16 v[130:133], v[74:77], v[182:185], v[130:133]
	v_mfma_f32_16x16x32_bf16 v[110:113], v[66:69], v[190:193], v[110:113]
	v_mfma_f32_16x16x32_bf16 v[106:109], v[74:77], v[190:193], v[106:109]
	v_mfma_f32_16x16x32_bf16 v[98:101], v[66:69], v[198:201], v[98:101]
	v_mfma_f32_16x16x32_bf16 v[94:97], v[74:77], v[198:201], v[94:97]
	v_mfma_f32_16x16x32_bf16 v[142:145], v[70:73], v[178:181], v[142:145]
	v_mfma_f32_16x16x32_bf16 v[138:141], v[102:105], v[178:181], v[138:141]
	v_mfma_f32_16x16x32_bf16 v[134:137], v[70:73], v[186:189], v[134:137]
	v_mfma_f32_16x16x32_bf16 v[130:133], v[102:105], v[186:189], v[130:133]
	v_mfma_f32_16x16x32_bf16 v[110:113], v[70:73], v[194:197], v[110:113]
	v_mfma_f32_16x16x32_bf16 v[106:109], v[102:105], v[194:197], v[106:109]
	v_mfma_f32_16x16x32_bf16 v[98:101], v[70:73], v[202:205], v[98:101]
	v_mfma_f32_16x16x32_bf16 v[94:97], v[102:105], v[202:205], v[94:97]
	v_mfma_f32_16x16x32_bf16 v[126:129], v[152:155], v[174:177], v[126:129]
	v_mfma_f32_16x16x32_bf16 v[122:125], v[166:169], v[174:177], v[122:125]
	v_mfma_f32_16x16x32_bf16 v[118:121], v[152:155], v[182:185], v[118:121]
	v_mfma_f32_16x16x32_bf16 v[114:117], v[166:169], v[182:185], v[114:117]
	v_mfma_f32_16x16x32_bf16 v[90:93], v[152:155], v[190:193], v[90:93]
	v_mfma_f32_16x16x32_bf16 v[86:89], v[166:169], v[190:193], v[86:89]
	v_mfma_f32_16x16x32_bf16 v[82:85], v[152:155], v[198:201], v[82:85]
	v_mfma_f32_16x16x32_bf16 v[78:81], v[166:169], v[198:201], v[78:81]
	v_mfma_f32_16x16x32_bf16 v[126:129], v[156:159], v[178:181], v[126:129]
	v_mfma_f32_16x16x32_bf16 v[122:125], v[170:173], v[178:181], v[122:125]
	v_mfma_f32_16x16x32_bf16 v[118:121], v[156:159], v[186:189], v[118:121]
	v_mfma_f32_16x16x32_bf16 v[114:117], v[170:173], v[186:189], v[114:117]
	v_mfma_f32_16x16x32_bf16 v[90:93], v[156:159], v[194:197], v[90:93]
	v_mfma_f32_16x16x32_bf16 v[86:89], v[170:173], v[194:197], v[86:89]
	v_mfma_f32_16x16x32_bf16 v[82:85], v[156:159], v[202:205], v[82:85]
	s_setprio 0
	v_mfma_f32_16x16x32_bf16 v[78:81], v[170:173], v[202:205], v[78:81]
	s_barrier
	s_add_i32 s30, s30, s12
	v_lshl_add_u64 v[206:207], s[6:7], 0, v[0:1]
	s_mov_b32 m0, s30
	ds_read_b128 v[174:177], v164 offset:16384
	ds_read_b128 v[178:181], v164 offset:17408
	ds_read_b128 v[182:185], v164 offset:18432
	ds_read_b128 v[186:189], v164 offset:19456
	ds_read_b128 v[190:193], v164 offset:20480
	ds_read_b128 v[194:197], v164 offset:21504
	ds_read_b128 v[198:201], v164 offset:22528
	ds_read_b128 v[202:205], v164 offset:23552
	global_load_lds_dwordx4 v[206:207], off
	s_add_i32 m0, s30, 0x2000
	s_add_u32 s30, s6, 0x158000
	v_lshl_add_u64 v[208:209], s[6:7], 0, v[146:147]
	s_addc_u32 s31, s7, 0
	s_add_i32 s34, s34, s12
	global_load_lds_dwordx4 v[208:209], off
	v_lshl_add_u64 v[210:211], s[30:31], 0, v[0:1]
	s_mov_b32 m0, s34
	v_lshl_add_u64 v[212:213], s[56:57], 0, v[146:147]
	global_load_lds_dwordx4 v[210:211], off
	s_add_i32 m0, s34, 0x2000
	v_lshl_add_u64 v[210:211], s[30:31], 0, v[146:147]
	global_load_lds_dwordx4 v[210:211], off
	s_mov_b32 m0, s13
	v_lshl_add_u64 v[210:211], s[56:57], 0, v[0:1]
	global_load_lds_dwordx4 v[210:211], off
	s_mov_b32 m0, s24
	s_nop 0
	global_load_lds_dwordx4 v[212:213], off
	s_setprio 1
	s_waitcnt vmcnt(8) lgkmcnt(0)
	s_barrier
; #define PG8_STAGE(bufoff, gbase, voff) do { _Pragma("unroll") for (int _i = 0; _i < 2; ++_i) \
;         __builtin_amdgcn_global_load_lds((const unsigned*)((const char*)(gbase) + (voff)[_i]), (LAS unsigned*)(lds + (bufoff) + ldsw + _i * 8192), 16, 0, 0); } while (0)
; #define PG8_LDA(dst, b, h) do { _Pragma("unroll") for (int m = 0; m < 4; ++m) _Pragma("unroll") for (int k = 0; k < 2; ++k) dst[m][k] = *(const LAS bf16x8*)(lds + PG8_SA(b, h) + aoff + m * 2048 + k * 1024); } while (0)
; #define PG8_LDB(dst, b, h) do { _Pragma("unroll") for (int n = 0; n < 2; ++n) _Pragma("unroll") for (int k = 0; k < 2; ++k) dst[n][k] = *(const LAS bf16x8*)(lds + PG8_SB(b, h) + boff + n * 2048 + k * 1024); } while (0)
; #define PG8_MMA(ai, bj, At, Bt) do { __builtin_amdgcn_s_setprio(1); _Pragma("unroll") for (int m = 0; m < 4; ++m) _Pragma("unroll") for (int n = 0; n < 2; ++n) _Pragma("unroll") for (int k = 0; k < 2; ++k) \
;         acc[ai][bj][m][n] = __builtin_amdgcn_mfma_f32_16x16x32_bf16(Bt[n][k], At[m][k], acc[ai][bj][m][n], 0, 0, 0); __builtin_amdgcn_s_setprio(0); } while (0)
; #define PG8_WAIT_V(n) asm volatile("s_waitcnt vmcnt(" #n ")" ::: "memory")
; #define PG8_WAIT_L(n) asm volatile("s_waitcnt lgkmcnt(" #n ")" ::: "memory")
; #define PG8_BAR __builtin_amdgcn_s_barrier()
; #define PG8_SCHED __builtin_amdgcn_sched_barrier(0)
; template <class Epi, int AMODE>
; __device__ __forceinline__ void gemm_phase(LAS unsigned char* lds, const Gemm g, const StaticOrder& S, const Epi& E, int stagger_us, int tid_in) {
;     ...
;             PG8_WAIT_V(8); PG8_WAIT_L(0); PG8_BAR; PG8_MMA(1, 0, At, B0); PG8_MMA(1, 1, At, B1); PG8_BAR; PG8_SCHED;
;             PG8_LDB(B0, 1, 0); PG8_LDB(B1, 1, 1); PG8_SCHED; PG8_LDA(At, 1, 0); PG8_STAGE(PG8_SA(0, 1), a2 + hstepA, voffA);
;             PG8_WAIT_V(8); PG8_WAIT_L(0); PG8_BAR; PG8_MMA(0, 0, At, B0); PG8_MMA(0, 1, At, B1); PG8_BAR; PG8_SCHED;
	v_mfma_f32_16x16x32_bf16 v[62:65], v[66:69], v[174:177], v[62:65]
	v_mfma_f32_16x16x32_bf16 v[58:61], v[74:77], v[174:177], v[58:61]
	v_mfma_f32_16x16x32_bf16 v[54:57], v[66:69], v[182:185], v[54:57]
	v_mfma_f32_16x16x32_bf16 v[50:53], v[74:77], v[182:185], v[50:53]
	v_mfma_f32_16x16x32_bf16 v[30:33], v[66:69], v[190:193], v[30:33]
	v_mfma_f32_16x16x32_bf16 v[26:29], v[74:77], v[190:193], v[26:29]
	v_mfma_f32_16x16x32_bf16 v[22:25], v[66:69], v[198:201], v[22:25]
	v_mfma_f32_16x16x32_bf16 v[10:13], v[74:77], v[198:201], v[10:13]
	v_mfma_f32_16x16x32_bf16 v[62:65], v[70:73], v[178:181], v[62:65]
	v_mfma_f32_16x16x32_bf16 v[58:61], v[102:105], v[178:181], v[58:61]
	v_mfma_f32_16x16x32_bf16 v[54:57], v[70:73], v[186:189], v[54:57]
	v_mfma_f32_16x16x32_bf16 v[50:53], v[102:105], v[186:189], v[50:53]
	v_mfma_f32_16x16x32_bf16 v[30:33], v[70:73], v[194:197], v[30:33]
	v_mfma_f32_16x16x32_bf16 v[26:29], v[102:105], v[194:197], v[26:29]
	v_mfma_f32_16x16x32_bf16 v[22:25], v[70:73], v[202:205], v[22:25]
	v_mfma_f32_16x16x32_bf16 v[10:13], v[102:105], v[202:205], v[10:13]
	v_mfma_f32_16x16x32_bf16 v[46:49], v[152:155], v[174:177], v[46:49]
	v_mfma_f32_16x16x32_bf16 v[42:45], v[166:169], v[174:177], v[42:45]
	v_mfma_f32_16x16x32_bf16 v[38:41], v[152:155], v[182:185], v[38:41]
	v_mfma_f32_16x16x32_bf16 v[34:37], v[166:169], v[182:185], v[34:37]
	v_mfma_f32_16x16x32_bf16 v[18:21], v[152:155], v[190:193], v[18:21]
	v_mfma_f32_16x16x32_bf16 v[14:17], v[166:169], v[190:193], v[14:17]
	v_mfma_f32_16x16x32_bf16 v[6:9], v[152:155], v[198:201], v[6:9]
	v_mfma_f32_16x16x32_bf16 v[2:5], v[166:169], v[198:201], v[2:5]
	v_mfma_f32_16x16x32_bf16 v[46:49], v[156:159], v[178:181], v[46:49]
	v_mfma_f32_16x16x32_bf16 v[42:45], v[170:173], v[178:181], v[42:45]
	v_mfma_f32_16x16x32_bf16 v[38:41], v[156:159], v[186:189], v[38:41]
	v_mfma_f32_16x16x32_bf16 v[34:37], v[170:173], v[186:189], v[34:37]
	v_mfma_f32_16x16x32_bf16 v[18:21], v[156:159], v[194:197], v[18:21]
	v_mfma_f32_16x16x32_bf16 v[14:17], v[170:173], v[194:197], v[14:17]
	v_mfma_f32_16x16x32_bf16 v[6:9], v[156:159], v[202:205], v[6:9]
	s_setprio 0
	v_mfma_f32_16x16x32_bf16 v[2:5], v[170:173], v[202:205], v[2:5]
	s_barrier
	s_add_i32 s34, 0, 0x18000
	s_add_i32 s35, 0, 0x1c000
	v_add_u32_e32 v102, s34, v162
	v_add_u32_e32 v165, s35, v162
	ds_read_b128 v[66:69], v102
	ds_read_b128 v[70:73], v102 offset:1024
	ds_read_b128 v[74:77], v102 offset:2048
	ds_read_b128 v[102:105], v102 offset:3072
	ds_read_b128 v[152:155], v165
	ds_read_b128 v[156:159], v165 offset:1024
	ds_read_b128 v[166:169], v165 offset:2048
	ds_read_b128 v[170:173], v165 offset:3072
	s_add_u32 s30, s56, 0x158000
	s_addc_u32 s31, s57, 0
	s_mov_b32 m0, s25
	v_lshl_add_u64 v[214:215], s[30:31], 0, v[0:1]
	ds_read_b128 v[174:177], v164 offset:32768
	ds_read_b128 v[178:181], v164 offset:33792
	ds_read_b128 v[182:185], v164 offset:34816
	ds_read_b128 v[186:189], v164 offset:35840
	ds_read_b128 v[190:193], v164 offset:36864
	ds_read_b128 v[194:197], v164 offset:37888
	ds_read_b128 v[198:201], v164 offset:38912
	ds_read_b128 v[202:205], v164 offset:39936
	global_load_lds_dwordx4 v[214:215], off
	s_mov_b32 m0, s66
	v_lshl_add_u64 v[214:215], s[30:31], 0, v[146:147]
	global_load_lds_dwordx4 v[214:215], off
	s_setprio 1
	s_waitcnt vmcnt(8) lgkmcnt(0)
	s_barrier
	v_mfma_f32_16x16x32_bf16 v[142:145], v[66:69], v[174:177], v[142:145]
	v_mfma_f32_16x16x32_bf16 v[138:141], v[74:77], v[174:177], v[138:141]
	v_mfma_f32_16x16x32_bf16 v[134:137], v[66:69], v[182:185], v[134:137]
	v_mfma_f32_16x16x32_bf16 v[130:133], v[74:77], v[182:185], v[130:133]
	v_mfma_f32_16x16x32_bf16 v[110:113], v[66:69], v[190:193], v[110:113]
	v_mfma_f32_16x16x32_bf16 v[106:109], v[74:77], v[190:193], v[106:109]
	v_mfma_f32_16x16x32_bf16 v[98:101], v[66:69], v[198:201], v[98:101]
	v_mfma_f32_16x16x32_bf16 v[94:97], v[74:77], v[198:201], v[94:97]
	v_mfma_f32_16x16x32_bf16 v[142:145], v[70:73], v[178:181], v[142:145]
	v_mfma_f32_16x16x32_bf16 v[138:141], v[102:105], v[178:181], v[138:141]
	v_mfma_f32_16x16x32_bf16 v[134:137], v[70:73], v[186:189], v[134:137]
	v_mfma_f32_16x16x32_bf16 v[130:133], v[102:105], v[186:189], v[130:133]
	v_mfma_f32_16x16x32_bf16 v[110:113], v[70:73], v[194:197], v[110:113]
	v_mfma_f32_16x16x32_bf16 v[106:109], v[102:105], v[194:197], v[106:109]
	v_mfma_f32_16x16x32_bf16 v[98:101], v[70:73], v[202:205], v[98:101]
	v_mfma_f32_16x16x32_bf16 v[94:97], v[102:105], v[202:205], v[94:97]
	v_mfma_f32_16x16x32_bf16 v[126:129], v[152:155], v[174:177], v[126:129]
	v_mfma_f32_16x16x32_bf16 v[122:125], v[166:169], v[174:177], v[122:125]
	v_mfma_f32_16x16x32_bf16 v[118:121], v[152:155], v[182:185], v[118:121]
	v_mfma_f32_16x16x32_bf16 v[114:117], v[166:169], v[182:185], v[114:117]
	v_mfma_f32_16x16x32_bf16 v[90:93], v[152:155], v[190:193], v[90:93]
	v_mfma_f32_16x16x32_bf16 v[86:89], v[166:169], v[190:193], v[86:89]
	v_mfma_f32_16x16x32_bf16 v[82:85], v[152:155], v[198:201], v[82:85]
	v_mfma_f32_16x16x32_bf16 v[78:81], v[166:169], v[198:201], v[78:81]
	v_mfma_f32_16x16x32_bf16 v[126:129], v[156:159], v[178:181], v[126:129]
	v_mfma_f32_16x16x32_bf16 v[122:125], v[170:173], v[178:181], v[122:125]
	v_mfma_f32_16x16x32_bf16 v[118:121], v[156:159], v[186:189], v[118:121]
	v_mfma_f32_16x16x32_bf16 v[114:117], v[170:173], v[186:189], v[114:117]
	v_mfma_f32_16x16x32_bf16 v[90:93], v[156:159], v[194:197], v[90:93]
	v_mfma_f32_16x16x32_bf16 v[86:89], v[170:173], v[194:197], v[86:89]
	v_mfma_f32_16x16x32_bf16 v[82:85], v[156:159], v[202:205], v[82:85]
	s_setprio 0
	v_mfma_f32_16x16x32_bf16 v[78:81], v[170:173], v[202:205], v[78:81]
	s_barrier
; #define PG8_STAGE(bufoff, gbase, voff) do { _Pragma("unroll") for (int _i = 0; _i < 2; ++_i) \
;         __builtin_amdgcn_global_load_lds((const unsigned*)((const char*)(gbase) + (voff)[_i]), (LAS unsigned*)(lds + (bufoff) + ldsw + _i * 8192), 16, 0, 0); } while (0)
; #define PG8_LDA(dst, b, h) do { _Pragma("unroll") for (int m = 0; m < 4; ++m) _Pragma("unroll") for (int k = 0; k < 2; ++k) dst[m][k] = *(const LAS bf16x8*)(lds + PG8_SA(b, h) + aoff + m * 2048 + k * 1024); } while (0)
; #define PG8_MMA(ai, bj, At, Bt) do { __builtin_amdgcn_s_setprio(1); _Pragma("unroll") for (int m = 0; m < 4; ++m) _Pragma("unroll") for (int n = 0; n < 2; ++n) _Pragma("unroll") for (int k = 0; k < 2; ++k) \
;         acc[ai][bj][m][n] = __builtin_amdgcn_mfma_f32_16x16x32_bf16(Bt[n][k], At[m][k], acc[ai][bj][m][n], 0, 0, 0); __builtin_amdgcn_s_setprio(0); } while (0)
; #define PG8_WAIT_V(n) asm volatile("s_waitcnt vmcnt(" #n ")" ::: "memory")
; #define PG8_WAIT_L(n) asm volatile("s_waitcnt lgkmcnt(" #n ")" ::: "memory")
; #define PG8_BAR __builtin_amdgcn_s_barrier()
; #define PG8_SCHED __builtin_amdgcn_sched_barrier(0)
; template <class Epi, int AMODE>
; __device__ __forceinline__ void gemm_phase(LAS unsigned char* lds, const Gemm g, const StaticOrder& S, const Epi& E, int stagger_us, int tid_in) {
;     ...
;             PG8_LDA(At, 1, 1); PG8_STAGE(PG8_SB(1, 0), b3, voffB); PG8_STAGE(PG8_SB(1, 1), b3 + hstepB, voffB); PG8_STAGE(PG8_SA(1, 0), a3, voffA);
;             PG8_WAIT_V(8); PG8_WAIT_L(0); PG8_BAR; PG8_MMA(1, 0, At, B0); PG8_MMA(1, 1, At, B1); PG8_BAR; PG8_SCHED;
;         }
;         if (wr == 0) PG8_BAR;
	s_add_i32 s30, s34, s12
	v_lshl_add_u64 v[206:207], v[206:207], 0, s[74:75]
	s_mov_b32 m0, s30
	ds_read_b128 v[174:177], v164 offset:49152
	ds_read_b128 v[178:181], v164 offset:50176
	ds_read_b128 v[182:185], v164 offset:51200
	ds_read_b128 v[186:189], v164 offset:52224
	ds_read_b128 v[190:193], v164 offset:53248
	ds_read_b128 v[194:197], v164 offset:54272
	ds_read_b128 v[198:201], v164 offset:55296
	ds_read_b128 v[202:205], v164 offset:56320
	global_load_lds_dwordx4 v[206:207], off
	s_add_i32 m0, s30, 0x2000
	s_add_u32 s6, s6, 0x158080
	v_lshl_add_u64 v[206:207], v[208:209], 0, s[74:75]
	s_addc_u32 s7, s7, 0
	s_add_i32 s30, s35, s12
	global_load_lds_dwordx4 v[206:207], off
	s_mov_b32 m0, s30
	v_lshl_add_u64 v[206:207], s[6:7], 0, v[0:1]
	global_load_lds_dwordx4 v[206:207], off
	s_add_i32 m0, s30, 0x2000
	v_lshl_add_u64 v[206:207], s[6:7], 0, v[146:147]
	global_load_lds_dwordx4 v[206:207], off
	s_mov_b32 m0, s67
	v_lshl_add_u64 v[206:207], v[210:211], 0, s[74:75]
	global_load_lds_dwordx4 v[206:207], off
	s_mov_b32 m0, s69
	v_lshl_add_u64 v[206:207], v[212:213], 0, s[74:75]
	global_load_lds_dwordx4 v[206:207], off
	s_setprio 1
	s_waitcnt vmcnt(8) lgkmcnt(0)
	s_barrier
	v_mfma_f32_16x16x32_bf16 v[62:65], v[66:69], v[174:177], v[62:65]
	v_mfma_f32_16x16x32_bf16 v[58:61], v[74:77], v[174:177], v[58:61]
	v_mfma_f32_16x16x32_bf16 v[54:57], v[66:69], v[182:185], v[54:57]
	v_mfma_f32_16x16x32_bf16 v[50:53], v[74:77], v[182:185], v[50:53]
	v_mfma_f32_16x16x32_bf16 v[30:33], v[66:69], v[190:193], v[30:33]
	v_mfma_f32_16x16x32_bf16 v[26:29], v[74:77], v[190:193], v[26:29]
	v_mfma_f32_16x16x32_bf16 v[22:25], v[66:69], v[198:201], v[22:25]
	v_mfma_f32_16x16x32_bf16 v[10:13], v[74:77], v[198:201], v[10:13]
	v_mfma_f32_16x16x32_bf16 v[62:65], v[70:73], v[178:181], v[62:65]
	v_mfma_f32_16x16x32_bf16 v[58:61], v[102:105], v[178:181], v[58:61]
	v_mfma_f32_16x16x32_bf16 v[54:57], v[70:73], v[186:189], v[54:57]
	v_mfma_f32_16x16x32_bf16 v[50:53], v[102:105], v[186:189], v[50:53]
	v_mfma_f32_16x16x32_bf16 v[30:33], v[70:73], v[194:197], v[30:33]
	v_mfma_f32_16x16x32_bf16 v[26:29], v[102:105], v[194:197], v[26:29]
	v_mfma_f32_16x16x32_bf16 v[22:25], v[70:73], v[202:205], v[22:25]
	v_mfma_f32_16x16x32_bf16 v[10:13], v[102:105], v[202:205], v[10:13]
	v_mfma_f32_16x16x32_bf16 v[46:49], v[152:155], v[174:177], v[46:49]
	v_mfma_f32_16x16x32_bf16 v[42:45], v[166:169], v[174:177], v[42:45]
	v_mfma_f32_16x16x32_bf16 v[38:41], v[152:155], v[182:185], v[38:41]
	v_mfma_f32_16x16x32_bf16 v[34:37], v[166:169], v[182:185], v[34:37]
	v_mfma_f32_16x16x32_bf16 v[18:21], v[152:155], v[190:193], v[18:21]
	v_mfma_f32_16x16x32_bf16 v[14:17], v[166:169], v[190:193], v[14:17]
	v_mfma_f32_16x16x32_bf16 v[6:9], v[152:155], v[198:201], v[6:9]
	v_mfma_f32_16x16x32_bf16 v[2:5], v[166:169], v[198:201], v[2:5]
	v_mfma_f32_16x16x32_bf16 v[46:49], v[156:159], v[178:181], v[46:49]
	v_mfma_f32_16x16x32_bf16 v[42:45], v[170:173], v[178:181], v[42:45]
	v_mfma_f32_16x16x32_bf16 v[38:41], v[156:159], v[186:189], v[38:41]
	v_mfma_f32_16x16x32_bf16 v[34:37], v[170:173], v[186:189], v[34:37]
	v_mfma_f32_16x16x32_bf16 v[18:21], v[156:159], v[194:197], v[18:21]
	v_mfma_f32_16x16x32_bf16 v[14:17], v[170:173], v[194:197], v[14:17]
	v_mfma_f32_16x16x32_bf16 v[6:9], v[156:159], v[202:205], v[6:9]
	s_setprio 0
	v_mfma_f32_16x16x32_bf16 v[2:5], v[170:173], v[202:205], v[2:5]
	s_barrier
	s_add_i32 s29, s29, 2
	s_add_u32 s27, s27, 0x100
	s_addc_u32 s28, s28, 0
	s_cmpk_gt_u32 s29, 0x53
	s_mov_b64 s[54:55], s[4:5]
	s_cbranch_scc0 .LBB0_1476
	s_and_b64 vcc, exec, s[46:47]
	s_cbranch_vccz .LBB0_1479
	s_barrier

; #define PG8_STAGE(bufoff, gbase, voff) do { _Pragma("unroll") for (int _i = 0; _i < 2; ++_i) \
;         __builtin_amdgcn_global_load_lds((const unsigned*)((const char*)(gbase) + (voff)[_i]), (LAS unsigned*)(lds + (bufoff) + ldsw + _i * 8192), 16, 0, 0); } while (0)
; #define PG8_LDA(dst, b, h) do { _Pragma("unroll") for (int m = 0; m < 4; ++m) _Pragma("unroll") for (int k = 0; k < 2; ++k) dst[m][k] = *(const LAS bf16x8*)(lds + PG8_SA(b, h) + aoff + m * 2048 + k * 1024); } while (0)
; #define PG8_LDB(dst, b, h) do { _Pragma("unroll") for (int n = 0; n < 2; ++n) _Pragma("unroll") for (int k = 0; k < 2; ++k) dst[n][k] = *(const LAS bf16x8*)(lds + PG8_SB(b, h) + boff + n * 2048 + k * 1024); } while (0)
; #define PG8_MMA(ai, bj, At, Bt) do { __builtin_amdgcn_s_setprio(1); _Pragma("unroll") for (int m = 0; m < 4; ++m) _Pragma("unroll") for (int n = 0; n < 2; ++n) _Pragma("unroll") for (int k = 0; k < 2; ++k) \
;         acc[ai][bj][m][n] = __builtin_amdgcn_mfma_f32_16x16x32_bf16(Bt[n][k], At[m][k], acc[ai][bj][m][n], 0, 0, 0); __builtin_amdgcn_s_setprio(0); } while (0)
; #define PG8_WAIT_V(n) asm volatile("s_waitcnt vmcnt(" #n ")" ::: "memory")
; #define PG8_WAIT_L(n) asm volatile("s_waitcnt lgkmcnt(" #n ")" ::: "memory")
; #define PG8_BAR __builtin_amdgcn_s_barrier()
; #define PG8_SCHED __builtin_amdgcn_sched_barrier(0)
; template <class Epi, int AMODE>
; __device__ __forceinline__ void gemm_phase(LAS unsigned char* lds, const Gemm g, const StaticOrder& S, const Epi& E, int stagger_us, int tid_in) {
;     ...
;             const bool last = (t == nt - 2);
;             const char* a1 = cA + (size_t)(t + 1) * kstep;
;             const char* a2 = last ? nA : cA + (size_t)(t + 2) * kstep; const char* b2 = last ? nB : cB + (size_t)(t + 2) * kstep;
;             const char* a3 = a2 + kstep; const char* b3 = b2 + kstep;
;             PG8_LDB(B0, 0, 0); PG8_LDB(B1, 0, 1); PG8_SCHED; PG8_LDA(At, 0, 0); PG8_STAGE(PG8_SA(1, 1), a1 + hstepA, voffA);
;             PG8_WAIT_V(8); PG8_WAIT_L(0); PG8_BAR; PG8_MMA(0, 0, At, B0); PG8_MMA(0, 1, At, B1); PG8_BAR; PG8_SCHED;
;             PG8_LDA(At, 0, 1); PG8_STAGE(PG8_SB(0, 0), b2, voffB); PG8_STAGE(PG8_SB(0, 1), b2 + hstepB, voffB); PG8_STAGE(PG8_SA(0, 0), a2, voffA);
;             PG8_WAIT_V(8); PG8_WAIT_L(0); PG8_BAR; PG8_MMA(1, 0, At, B0); PG8_MMA(1, 1, At, B1); PG8_BAR; PG8_SCHED;
.LBB0_1498:
	s_add_u32 s4, s46, 0x100
	s_addc_u32 s5, s47, 0
	s_add_i32 s30, 0, 0x10000
	s_cmpk_eq_i32 s29, 0x52
	s_cselect_b32 s59, s41, s5
	s_cselect_b32 s58, s40, s4
	s_cselect_b32 s7, s57, s28
	s_cselect_b32 s6, s56, s27
	s_add_i32 s34, 0, 0x14000
	v_add_u32_e32 v62, s30, v209
	v_add_u32_e32 v158, s34, v209
	ds_read_b128 v[50:53], v62
	ds_read_b128 v[54:57], v62 offset:1024
	ds_read_b128 v[58:61], v62 offset:2048
	ds_read_b128 v[62:65], v62 offset:3072
	ds_read_b128 v[146:149], v158
	ds_read_b128 v[150:153], v158 offset:1024
	ds_read_b128 v[154:157], v158 offset:2048
	ds_read_b128 v[158:161], v158 offset:3072
	v_lshl_add_u64 v[200:201], s[46:47], 0, v[176:177]
	s_add_i32 m0, s13, 0xc000
	ds_read_b128 v[162:165], v215
	ds_read_b128 v[166:169], v215 offset:1024
	ds_read_b128 v[170:173], v215 offset:2048
	ds_read_b128 v[180:183], v215 offset:3072
	ds_read_b128 v[184:187], v215 offset:4096
	ds_read_b128 v[188:191], v215 offset:5120
	ds_read_b128 v[192:195], v215 offset:6144
	ds_read_b128 v[196:199], v215 offset:7168
	global_load_lds_dwordx4 v[200:201], off
	s_add_i32 m0, s13, 0xe000
	v_lshl_add_u64 v[200:201], s[46:47], 0, v[178:179]
	global_load_lds_dwordx4 v[200:201], off
	s_setprio 1
	s_waitcnt vmcnt(8) lgkmcnt(0)
	s_barrier
	v_mfma_f32_16x16x32_bf16 v[142:145], v[50:53], v[162:165], v[142:145]
	v_mfma_f32_16x16x32_bf16 v[138:141], v[58:61], v[162:165], v[138:141]
	v_mfma_f32_16x16x32_bf16 v[126:129], v[50:53], v[170:173], v[126:129]
	v_mfma_f32_16x16x32_bf16 v[122:125], v[58:61], v[170:173], v[122:125]
	v_mfma_f32_16x16x32_bf16 v[110:113], v[50:53], v[184:187], v[110:113]
	v_mfma_f32_16x16x32_bf16 v[106:109], v[58:61], v[184:187], v[106:109]
	v_mfma_f32_16x16x32_bf16 v[94:97], v[50:53], v[192:195], v[94:97]
	v_mfma_f32_16x16x32_bf16 v[90:93], v[58:61], v[192:195], v[90:93]
	v_mfma_f32_16x16x32_bf16 v[142:145], v[54:57], v[166:169], v[142:145]
	v_mfma_f32_16x16x32_bf16 v[138:141], v[62:65], v[166:169], v[138:141]
	v_mfma_f32_16x16x32_bf16 v[126:129], v[54:57], v[180:183], v[126:129]
	v_mfma_f32_16x16x32_bf16 v[122:125], v[62:65], v[180:183], v[122:125]
	v_mfma_f32_16x16x32_bf16 v[110:113], v[54:57], v[188:191], v[110:113]
	v_mfma_f32_16x16x32_bf16 v[106:109], v[62:65], v[188:191], v[106:109]
	v_mfma_f32_16x16x32_bf16 v[94:97], v[54:57], v[196:199], v[94:97]
	v_mfma_f32_16x16x32_bf16 v[90:93], v[62:65], v[196:199], v[90:93]
	v_mfma_f32_16x16x32_bf16 v[134:137], v[146:149], v[162:165], v[134:137]
	v_mfma_f32_16x16x32_bf16 v[130:133], v[154:157], v[162:165], v[130:133]
	v_mfma_f32_16x16x32_bf16 v[118:121], v[146:149], v[170:173], v[118:121]
	v_mfma_f32_16x16x32_bf16 v[114:117], v[154:157], v[170:173], v[114:117]
	v_mfma_f32_16x16x32_bf16 v[102:105], v[146:149], v[184:187], v[102:105]
	v_mfma_f32_16x16x32_bf16 v[98:101], v[154:157], v[184:187], v[98:101]
	v_mfma_f32_16x16x32_bf16 v[86:89], v[146:149], v[192:195], v[86:89]
	v_mfma_f32_16x16x32_bf16 v[82:85], v[154:157], v[192:195], v[82:85]
	v_mfma_f32_16x16x32_bf16 v[134:137], v[150:153], v[166:169], v[134:137]
	v_mfma_f32_16x16x32_bf16 v[130:133], v[158:161], v[166:169], v[130:133]
	v_mfma_f32_16x16x32_bf16 v[118:121], v[150:153], v[180:183], v[118:121]
	v_mfma_f32_16x16x32_bf16 v[114:117], v[158:161], v[180:183], v[114:117]
	v_mfma_f32_16x16x32_bf16 v[102:105], v[150:153], v[188:191], v[102:105]
	v_mfma_f32_16x16x32_bf16 v[98:101], v[158:161], v[188:191], v[98:101]
	v_mfma_f32_16x16x32_bf16 v[86:89], v[150:153], v[196:199], v[86:89]
	s_setprio 0
	v_mfma_f32_16x16x32_bf16 v[82:85], v[158:161], v[196:199], v[82:85]
	s_barrier
	s_add_i32 s30, s30, s12
	v_lshl_add_u64 v[200:201], s[6:7], 0, v[0:1]
	s_mov_b32 m0, s30
	ds_read_b128 v[162:165], v215 offset:16384
	ds_read_b128 v[166:169], v215 offset:17408
	ds_read_b128 v[170:173], v215 offset:18432
	ds_read_b128 v[180:183], v215 offset:19456
	ds_read_b128 v[184:187], v215 offset:20480
	ds_read_b128 v[188:191], v215 offset:21504
	ds_read_b128 v[192:195], v215 offset:22528
	ds_read_b128 v[196:199], v215 offset:23552
	global_load_lds_dwordx4 v[200:201], off
	s_add_i32 m0, s30, 0x2000
	s_add_u32 s30, s6, 0x158000
	v_lshl_add_u64 v[202:203], s[6:7], 0, v[174:175]
	s_addc_u32 s31, s7, 0
	s_add_i32 s34, s34, s12
	global_load_lds_dwordx4 v[202:203], off
	v_lshl_add_u64 v[204:205], s[30:31], 0, v[0:1]
	s_mov_b32 m0, s34
	v_lshl_add_u64 v[206:207], s[58:59], 0, v[174:175]
	global_load_lds_dwordx4 v[204:205], off
	s_add_i32 m0, s34, 0x2000
	v_lshl_add_u64 v[204:205], s[30:31], 0, v[174:175]
	global_load_lds_dwordx4 v[204:205], off
	s_mov_b32 m0, s13
	v_lshl_add_u64 v[204:205], s[58:59], 0, v[0:1]
	global_load_lds_dwordx4 v[204:205], off
	s_mov_b32 m0, s24
	s_nop 0
	global_load_lds_dwordx4 v[206:207], off
	s_setprio 1
	s_waitcnt vmcnt(8) lgkmcnt(0)
	s_barrier
; #define PG8_STAGE(bufoff, gbase, voff) do { _Pragma("unroll") for (int _i = 0; _i < 2; ++_i) \
;         __builtin_amdgcn_global_load_lds((const unsigned*)((const char*)(gbase) + (voff)[_i]), (LAS unsigned*)(lds + (bufoff) + ldsw + _i * 8192), 16, 0, 0); } while (0)
; #define PG8_LDA(dst, b, h) do { _Pragma("unroll") for (int m = 0; m < 4; ++m) _Pragma("unroll") for (int k = 0; k < 2; ++k) dst[m][k] = *(const LAS bf16x8*)(lds + PG8_SA(b, h) + aoff + m * 2048 + k * 1024); } while (0)
; #define PG8_LDB(dst, b, h) do { _Pragma("unroll") for (int n = 0; n < 2; ++n) _Pragma("unroll") for (int k = 0; k < 2; ++k) dst[n][k] = *(const LAS bf16x8*)(lds + PG8_SB(b, h) + boff + n * 2048 + k * 1024); } while (0)
; #define PG8_MMA(ai, bj, At, Bt) do { __builtin_amdgcn_s_setprio(1); _Pragma("unroll") for (int m = 0; m < 4; ++m) _Pragma("unroll") for (int n = 0; n < 2; ++n) _Pragma("unroll") for (int k = 0; k < 2; ++k) \
;         acc[ai][bj][m][n] = __builtin_amdgcn_mfma_f32_16x16x32_bf16(Bt[n][k], At[m][k], acc[ai][bj][m][n], 0, 0, 0); __builtin_amdgcn_s_setprio(0); } while (0)
; #define PG8_WAIT_V(n) asm volatile("s_waitcnt vmcnt(" #n ")" ::: "memory")
; #define PG8_WAIT_L(n) asm volatile("s_waitcnt lgkmcnt(" #n ")" ::: "memory")
; #define PG8_BAR __builtin_amdgcn_s_barrier()
; #define PG8_SCHED __builtin_amdgcn_sched_barrier(0)
; template <class Epi, int AMODE>
; __device__ __forceinline__ void gemm_phase(LAS unsigned char* lds, const Gemm g, const StaticOrder& S, const Epi& E, int stagger_us, int tid_in) {
;     ...
;             PG8_WAIT_V(8); PG8_WAIT_L(0); PG8_BAR; PG8_MMA(1, 0, At, B0); PG8_MMA(1, 1, At, B1); PG8_BAR; PG8_SCHED;
;             PG8_LDB(B0, 1, 0); PG8_LDB(B1, 1, 1); PG8_SCHED; PG8_LDA(At, 1, 0); PG8_STAGE(PG8_SA(0, 1), a2 + hstepA, voffA);
;             PG8_WAIT_V(8); PG8_WAIT_L(0); PG8_BAR; PG8_MMA(0, 0, At, B0); PG8_MMA(0, 1, At, B1); PG8_BAR; PG8_SCHED;
	v_mfma_f32_16x16x32_bf16 v[78:81], v[50:53], v[162:165], v[78:81]
	v_mfma_f32_16x16x32_bf16 v[74:77], v[58:61], v[162:165], v[74:77]
	v_mfma_f32_16x16x32_bf16 v[46:49], v[50:53], v[170:173], v[46:49]
	v_mfma_f32_16x16x32_bf16 v[42:45], v[58:61], v[170:173], v[42:45]
	v_mfma_f32_16x16x32_bf16 v[30:33], v[50:53], v[184:187], v[30:33]
	v_mfma_f32_16x16x32_bf16 v[26:29], v[58:61], v[184:187], v[26:29]
	v_mfma_f32_16x16x32_bf16 v[14:17], v[50:53], v[192:195], v[14:17]
	v_mfma_f32_16x16x32_bf16 v[10:13], v[58:61], v[192:195], v[10:13]
	v_mfma_f32_16x16x32_bf16 v[78:81], v[54:57], v[166:169], v[78:81]
	v_mfma_f32_16x16x32_bf16 v[74:77], v[62:65], v[166:169], v[74:77]
	v_mfma_f32_16x16x32_bf16 v[46:49], v[54:57], v[180:183], v[46:49]
	v_mfma_f32_16x16x32_bf16 v[42:45], v[62:65], v[180:183], v[42:45]
	v_mfma_f32_16x16x32_bf16 v[30:33], v[54:57], v[188:191], v[30:33]
	v_mfma_f32_16x16x32_bf16 v[26:29], v[62:65], v[188:191], v[26:29]
	v_mfma_f32_16x16x32_bf16 v[14:17], v[54:57], v[196:199], v[14:17]
	v_mfma_f32_16x16x32_bf16 v[10:13], v[62:65], v[196:199], v[10:13]
	v_mfma_f32_16x16x32_bf16 v[38:41], v[146:149], v[170:173], v[38:41]
	v_mfma_f32_16x16x32_bf16 v[34:37], v[154:157], v[170:173], v[34:37]
	v_mfma_f32_16x16x32_bf16 v[22:25], v[146:149], v[184:187], v[22:25]
	v_mfma_f32_16x16x32_bf16 v[18:21], v[154:157], v[184:187], v[18:21]
	v_mfma_f32_16x16x32_bf16 v[6:9], v[146:149], v[192:195], v[6:9]
	v_mfma_f32_16x16x32_bf16 v[2:5], v[154:157], v[192:195], v[2:5]
	v_mfma_f32_16x16x32_bf16 v[50:53], v[146:149], v[162:165], v[70:73]
	v_mfma_f32_16x16x32_bf16 v[54:57], v[154:157], v[162:165], v[66:69]
	v_mfma_f32_16x16x32_bf16 v[38:41], v[150:153], v[180:183], v[38:41]
	v_mfma_f32_16x16x32_bf16 v[34:37], v[158:161], v[180:183], v[34:37]
	v_mfma_f32_16x16x32_bf16 v[22:25], v[150:153], v[188:191], v[22:25]
	v_mfma_f32_16x16x32_bf16 v[18:21], v[158:161], v[188:191], v[18:21]
	v_mfma_f32_16x16x32_bf16 v[6:9], v[150:153], v[196:199], v[6:9]
	v_mfma_f32_16x16x32_bf16 v[2:5], v[158:161], v[196:199], v[2:5]
	v_mfma_f32_16x16x32_bf16 v[50:53], v[150:153], v[166:169], v[50:53]
	s_setprio 0
	v_mfma_f32_16x16x32_bf16 v[54:57], v[158:161], v[166:169], v[54:57]
	s_barrier
	s_add_i32 s34, 0, 0x18000
	s_add_i32 s35, 0, 0x1c000
	v_add_u32_e32 v70, s34, v209
	v_add_u32_e32 v158, s35, v209
	ds_read_b128 v[58:61], v70
	ds_read_b128 v[62:65], v70 offset:1024
	ds_read_b128 v[66:69], v70 offset:2048
	ds_read_b128 v[70:73], v70 offset:3072
	ds_read_b128 v[146:149], v158
	ds_read_b128 v[150:153], v158 offset:1024
	ds_read_b128 v[154:157], v158 offset:2048
	ds_read_b128 v[158:161], v158 offset:3072
	s_add_u32 s30, s58, 0x158000
	s_addc_u32 s31, s59, 0
	s_mov_b32 m0, s25
	v_lshl_add_u64 v[210:211], s[30:31], 0, v[0:1]
	ds_read_b128 v[162:165], v215 offset:32768
	ds_read_b128 v[166:169], v215 offset:33792
	ds_read_b128 v[170:173], v215 offset:34816
	ds_read_b128 v[180:183], v215 offset:35840
	ds_read_b128 v[184:187], v215 offset:36864
	ds_read_b128 v[188:191], v215 offset:37888
	ds_read_b128 v[192:195], v215 offset:38912
	ds_read_b128 v[196:199], v215 offset:39936
	global_load_lds_dwordx4 v[210:211], off
	s_mov_b32 m0, s66
	v_lshl_add_u64 v[210:211], s[30:31], 0, v[174:175]
	global_load_lds_dwordx4 v[210:211], off
	s_setprio 1
	s_waitcnt vmcnt(8) lgkmcnt(0)
	s_barrier
	v_mfma_f32_16x16x32_bf16 v[142:145], v[58:61], v[162:165], v[142:145]
	v_mfma_f32_16x16x32_bf16 v[138:141], v[66:69], v[162:165], v[138:141]
	v_mfma_f32_16x16x32_bf16 v[126:129], v[58:61], v[170:173], v[126:129]
	v_mfma_f32_16x16x32_bf16 v[122:125], v[66:69], v[170:173], v[122:125]
	v_mfma_f32_16x16x32_bf16 v[110:113], v[58:61], v[184:187], v[110:113]
	v_mfma_f32_16x16x32_bf16 v[106:109], v[66:69], v[184:187], v[106:109]
	v_mfma_f32_16x16x32_bf16 v[94:97], v[58:61], v[192:195], v[94:97]
	v_mfma_f32_16x16x32_bf16 v[90:93], v[66:69], v[192:195], v[90:93]
	v_mfma_f32_16x16x32_bf16 v[142:145], v[62:65], v[166:169], v[142:145]
	v_mfma_f32_16x16x32_bf16 v[138:141], v[70:73], v[166:169], v[138:141]
	v_mfma_f32_16x16x32_bf16 v[126:129], v[62:65], v[180:183], v[126:129]
	v_mfma_f32_16x16x32_bf16 v[122:125], v[70:73], v[180:183], v[122:125]
	v_mfma_f32_16x16x32_bf16 v[110:113], v[62:65], v[188:191], v[110:113]
	v_mfma_f32_16x16x32_bf16 v[106:109], v[70:73], v[188:191], v[106:109]
	v_mfma_f32_16x16x32_bf16 v[94:97], v[62:65], v[196:199], v[94:97]
	v_mfma_f32_16x16x32_bf16 v[90:93], v[70:73], v[196:199], v[90:93]
	v_mfma_f32_16x16x32_bf16 v[134:137], v[146:149], v[162:165], v[134:137]
	v_mfma_f32_16x16x32_bf16 v[130:133], v[154:157], v[162:165], v[130:133]
	v_mfma_f32_16x16x32_bf16 v[118:121], v[146:149], v[170:173], v[118:121]
	v_mfma_f32_16x16x32_bf16 v[114:117], v[154:157], v[170:173], v[114:117]
	v_mfma_f32_16x16x32_bf16 v[102:105], v[146:149], v[184:187], v[102:105]
	v_mfma_f32_16x16x32_bf16 v[98:101], v[154:157], v[184:187], v[98:101]
	v_mfma_f32_16x16x32_bf16 v[86:89], v[146:149], v[192:195], v[86:89]
	v_mfma_f32_16x16x32_bf16 v[82:85], v[154:157], v[192:195], v[82:85]
	v_mfma_f32_16x16x32_bf16 v[134:137], v[150:153], v[166:169], v[134:137]
	v_mfma_f32_16x16x32_bf16 v[130:133], v[158:161], v[166:169], v[130:133]
	v_mfma_f32_16x16x32_bf16 v[118:121], v[150:153], v[180:183], v[118:121]
	v_mfma_f32_16x16x32_bf16 v[114:117], v[158:161], v[180:183], v[114:117]
	v_mfma_f32_16x16x32_bf16 v[102:105], v[150:153], v[188:191], v[102:105]
	v_mfma_f32_16x16x32_bf16 v[98:101], v[158:161], v[188:191], v[98:101]
	v_mfma_f32_16x16x32_bf16 v[86:89], v[150:153], v[196:199], v[86:89]
	s_setprio 0
	v_mfma_f32_16x16x32_bf16 v[82:85], v[158:161], v[196:199], v[82:85]
	s_barrier
; #define PG8_STAGE(bufoff, gbase, voff) do { _Pragma("unroll") for (int _i = 0; _i < 2; ++_i) \
;         __builtin_amdgcn_global_load_lds((const unsigned*)((const char*)(gbase) + (voff)[_i]), (LAS unsigned*)(lds + (bufoff) + ldsw + _i * 8192), 16, 0, 0); } while (0)
; #define PG8_LDA(dst, b, h) do { _Pragma("unroll") for (int m = 0; m < 4; ++m) _Pragma("unroll") for (int k = 0; k < 2; ++k) dst[m][k] = *(const LAS bf16x8*)(lds + PG8_SA(b, h) + aoff + m * 2048 + k * 1024); } while (0)
; #define PG8_MMA(ai, bj, At, Bt) do { __builtin_amdgcn_s_setprio(1); _Pragma("unroll") for (int m = 0; m < 4; ++m) _Pragma("unroll") for (int n = 0; n < 2; ++n) _Pragma("unroll") for (int k = 0; k < 2; ++k) \
;         acc[ai][bj][m][n] = __builtin_amdgcn_mfma_f32_16x16x32_bf16(Bt[n][k], At[m][k], acc[ai][bj][m][n], 0, 0, 0); __builtin_amdgcn_s_setprio(0); } while (0)
; #define PG8_WAIT_V(n) asm volatile("s_waitcnt vmcnt(" #n ")" ::: "memory")
; #define PG8_WAIT_L(n) asm volatile("s_waitcnt lgkmcnt(" #n ")" ::: "memory")
; #define PG8_BAR __builtin_amdgcn_s_barrier()
; #define PG8_SCHED __builtin_amdgcn_sched_barrier(0)
; template <class Epi, int AMODE>
; __device__ __forceinline__ void gemm_phase(LAS unsigned char* lds, const Gemm g, const StaticOrder& S, const Epi& E, int stagger_us, int tid_in) {
;     ...
;             PG8_LDA(At, 1, 1); PG8_STAGE(PG8_SB(1, 0), b3, voffB); PG8_STAGE(PG8_SB(1, 1), b3 + hstepB, voffB); PG8_STAGE(PG8_SA(1, 0), a3, voffA);
;             PG8_WAIT_V(8); PG8_WAIT_L(0); PG8_BAR; PG8_MMA(1, 0, At, B0); PG8_MMA(1, 1, At, B1); PG8_BAR; PG8_SCHED;
;         }
;         if (wr == 0) PG8_BAR;
	s_add_i32 s30, s34, s12
	v_lshl_add_u64 v[200:201], v[200:201], 0, s[74:75]
	s_mov_b32 m0, s30
	ds_read_b128 v[162:165], v215 offset:49152
	ds_read_b128 v[166:169], v215 offset:50176
	ds_read_b128 v[170:173], v215 offset:51200
	ds_read_b128 v[180:183], v215 offset:52224
	ds_read_b128 v[184:187], v215 offset:53248
	ds_read_b128 v[188:191], v215 offset:54272
	ds_read_b128 v[192:195], v215 offset:55296
	ds_read_b128 v[196:199], v215 offset:56320
	global_load_lds_dwordx4 v[200:201], off
	s_add_i32 m0, s30, 0x2000
	s_add_u32 s6, s6, 0x158080
	v_lshl_add_u64 v[200:201], v[202:203], 0, s[74:75]
	s_addc_u32 s7, s7, 0
	s_add_i32 s30, s35, s12
	global_load_lds_dwordx4 v[200:201], off
	s_mov_b32 m0, s30
	v_lshl_add_u64 v[200:201], s[6:7], 0, v[0:1]
	global_load_lds_dwordx4 v[200:201], off
	s_add_i32 m0, s30, 0x2000
	v_lshl_add_u64 v[200:201], s[6:7], 0, v[174:175]
	global_load_lds_dwordx4 v[200:201], off
	s_mov_b32 m0, s79
	v_lshl_add_u64 v[200:201], v[204:205], 0, s[74:75]
	global_load_lds_dwordx4 v[200:201], off
	s_mov_b32 m0, s83
	v_lshl_add_u64 v[200:201], v[206:207], 0, s[74:75]
	global_load_lds_dwordx4 v[200:201], off
	s_setprio 1
	s_waitcnt vmcnt(8) lgkmcnt(0)
	s_barrier
	v_mfma_f32_16x16x32_bf16 v[78:81], v[58:61], v[162:165], v[78:81]
	v_mfma_f32_16x16x32_bf16 v[74:77], v[66:69], v[162:165], v[74:77]
	v_mfma_f32_16x16x32_bf16 v[46:49], v[58:61], v[170:173], v[46:49]
	v_mfma_f32_16x16x32_bf16 v[42:45], v[66:69], v[170:173], v[42:45]
	v_mfma_f32_16x16x32_bf16 v[30:33], v[58:61], v[184:187], v[30:33]
	v_mfma_f32_16x16x32_bf16 v[26:29], v[66:69], v[184:187], v[26:29]
	v_mfma_f32_16x16x32_bf16 v[14:17], v[58:61], v[192:195], v[14:17]
	v_mfma_f32_16x16x32_bf16 v[10:13], v[66:69], v[192:195], v[10:13]
	v_mfma_f32_16x16x32_bf16 v[78:81], v[62:65], v[166:169], v[78:81]
	v_mfma_f32_16x16x32_bf16 v[74:77], v[70:73], v[166:169], v[74:77]
	v_mfma_f32_16x16x32_bf16 v[46:49], v[62:65], v[180:183], v[46:49]
	v_mfma_f32_16x16x32_bf16 v[42:45], v[70:73], v[180:183], v[42:45]
	v_mfma_f32_16x16x32_bf16 v[30:33], v[62:65], v[188:191], v[30:33]
	v_mfma_f32_16x16x32_bf16 v[26:29], v[70:73], v[188:191], v[26:29]
	v_mfma_f32_16x16x32_bf16 v[14:17], v[62:65], v[196:199], v[14:17]
	v_mfma_f32_16x16x32_bf16 v[10:13], v[70:73], v[196:199], v[10:13]
	v_mfma_f32_16x16x32_bf16 v[50:53], v[146:149], v[162:165], v[50:53]
	v_mfma_f32_16x16x32_bf16 v[70:73], v[150:153], v[166:169], v[50:53]
	v_mfma_f32_16x16x32_bf16 v[50:53], v[154:157], v[162:165], v[54:57]
	v_mfma_f32_16x16x32_bf16 v[38:41], v[146:149], v[170:173], v[38:41]
	v_mfma_f32_16x16x32_bf16 v[34:37], v[154:157], v[170:173], v[34:37]
	v_mfma_f32_16x16x32_bf16 v[22:25], v[146:149], v[184:187], v[22:25]
	v_mfma_f32_16x16x32_bf16 v[18:21], v[154:157], v[184:187], v[18:21]
	v_mfma_f32_16x16x32_bf16 v[6:9], v[146:149], v[192:195], v[6:9]
	v_mfma_f32_16x16x32_bf16 v[2:5], v[154:157], v[192:195], v[2:5]
	v_mfma_f32_16x16x32_bf16 v[66:69], v[158:161], v[166:169], v[50:53]
	v_mfma_f32_16x16x32_bf16 v[38:41], v[150:153], v[180:183], v[38:41]
	v_mfma_f32_16x16x32_bf16 v[34:37], v[158:161], v[180:183], v[34:37]
	v_mfma_f32_16x16x32_bf16 v[22:25], v[150:153], v[188:191], v[22:25]
	v_mfma_f32_16x16x32_bf16 v[18:21], v[158:161], v[188:191], v[18:21]
	v_mfma_f32_16x16x32_bf16 v[6:9], v[150:153], v[196:199], v[6:9]
	s_setprio 0
	v_mfma_f32_16x16x32_bf16 v[2:5], v[158:161], v[196:199], v[2:5]
	s_barrier
	s_add_i32 s29, s29, 2
	s_add_u32 s27, s27, 0x100
	s_addc_u32 s28, s28, 0
	s_cmpk_gt_u32 s29, 0x53
	s_mov_b64 s[46:47], s[4:5]
	s_cbranch_scc0 .LBB0_1498
	s_and_b64 vcc, exec, s[54:55]
	s_cbranch_vccz .LBB0_1501
	s_barrier
